# v26
# baseline (speedup 1.0000x reference)
.LBB0_263:
	s_add_u32 s8, s88, 0x114db700
	s_addc_u32 s9, s89, 0
	s_add_u32 s10, s88, 0x196db700
	s_addc_u32 s11, s89, 0
	s_add_u32 s12, s88, 0x19edb700
	s_addc_u32 s13, s89, 0
	s_lshl_b32 s6, s85, 5
	s_and_b32 s15, s6, 0x60
	s_add_i32 m0, s58, 0x18000
	v_lshl_add_u64 v[6:7], v[6:7], 0, s[54:55]
	s_lshl_b32 s14, s5, 6
	s_lshl_b32 s5, s5, 13
	s_lshl_b32 s16, s15, 7
	s_waitcnt vmcnt(4)
	s_barrier
	global_load_lds_dwordx4 v[6:7], off
	v_lshl_add_u64 v[4:5], v[4:5], 0, s[54:55]
	s_add_i32 m0, s58, 0x1a000
	s_add_i32 s62, s58, 0x8000
	s_add_i32 s63, s58, 0xa000
	global_load_lds_dwordx4 v[4:5], off
	v_lshl_add_u64 v[2:3], v[2:3], 0, s[54:55]
	s_mov_b32 m0, s62
	s_add_u32 s6, s26, 0x80080
	global_load_lds_dwordx4 v[2:3], off
	v_lshl_add_u64 v[0:1], v[0:1], 0, s[54:55]
	s_mov_b32 m0, s63
	s_addc_u32 s7, s27, 0
	global_load_lds_dwordx4 v[0:1], off
	s_add_i32 m0, s58, 0x1c000
	s_nop 0
	global_load_lds_dwordx4 v130, s[6:7]
	s_add_i32 m0, s58, 0x1e000
	v_lshlrev_b32_e32 v3, 2, v8
	global_load_lds_dwordx4 v134, s[6:7]
	v_lshrrev_b32_e32 v1, 1, v8
	v_and_b32_e32 v1, 24, v1
	v_and_b32_e32 v0, 15, v8
	v_lshlrev_b32_e32 v2, 1, v1
	v_or_b32_e32 v136, s15, v1
	v_mov_b32_e32 v1, 0x4f
	v_or_b32_e32 v137, s14, v0
	v_lshl_or_b32 v2, v0, 6, v2
	v_bitop3_b32 v0, s14, v1, v0 bitop3:0xc8
	v_subrev_u32_e32 v1, 64, v0
	v_cmp_lt_u32_e32 vcc, 64, v0
	v_and_b32_e32 v3, 32, v3
	s_waitcnt vmcnt(6)
	v_bitop3_b32 v4, v2, s5, v3 bitop3:0xde
	v_cndmask_b32_e32 v155, v0, v1, vcc
	v_mov_b32_e32 v0, 0x1000
	v_cndmask_b32_e32 v178, 0, v0, vcc
	v_mov_b32_e32 v0, 0x200
	v_cndmask_b32_e32 v0, 0, v0, vcc
	v_mov_b32_e32 v1, v179
	v_lshl_add_u64 v[140:141], s[10:11], 0, v[0:1]
	v_lshlrev_b32_e32 v0, 15, v12
	v_and_b32_e32 v0, 0xffff0000, v0
	v_lshl_add_u32 v0, v13, 12, v0
	v_and_b32_e32 v1, 1, v12
	v_lshl_or_b32 v0, v1, 6, v0
	v_lshl_add_u32 v144, v14, 1, v0
	v_lshlrev_b32_e32 v0, 15, v9
	v_and_b32_e32 v0, 0xffff0000, v0
	v_lshl_add_u32 v0, v10, 12, v0
	v_and_b32_e32 v1, 1, v9
	v_lshl_add_u64 v[138:139], s[12:13], 0, v[178:179]
	v_lshlrev_b32_e32 v178, 1, v136
	v_lshl_or_b32 v0, v1, 6, v0
	v_bitop3_b32 v154, v2, s16, v3 bitop3:0xde
	s_mov_b32 s66, 0
	v_lshl_add_u64 v[142:143], v[140:141], 0, v[178:179]
	v_mov_b32_e32 v145, v179
	v_lshl_add_u32 v146, v11, 1, v0
	v_mov_b32_e32 v147, v179
	v_add_u32_e32 v156, 0, v4
	s_barrier
	s_branch .LBB0_266

.LBB0_934:
	v_lshl_add_u64 v[8:9], s[8:9], 0, v[178:179]
	v_mov_b32_e32 v129, v179
	v_and_b32_e32 v7, 15, v3
	v_lshrrev_b32_e32 v16, 1, v3
	v_lshl_add_u64 v[10:11], s[8:9], 0, v[128:129]
	v_mov_b32_e32 v133, v179
	v_or_b32_e32 v138, s20, v7
	v_and_b32_e32 v139, 24, v16
	s_add_i32 m0, s22, 0x18000
	v_lshl_add_u64 v[8:9], v[8:9], 0, s[54:55]
	v_lshl_add_u64 v[12:13], s[6:7], 0, v[132:133]
	v_mov_b32_e32 v131, v179
	v_lshlrev_b32_e32 v16, 6, v138
	v_lshlrev_b32_e32 v17, 1, v139
	s_movk_i32 s10, 0x3c0
	s_waitcnt vmcnt(4)
	s_barrier
	global_load_lds_dwordx4 v[8:9], off
	v_lshl_add_u64 v[8:9], v[10:11], 0, s[54:55]
	s_add_i32 m0, s22, 0x1a000
	s_add_i32 s26, s22, 0x8000
	s_add_i32 s27, s22, 0xa000
	v_lshl_add_u64 v[14:15], s[6:7], 0, v[130:131]
	v_and_or_b32 v16, v16, s10, v17
	global_load_lds_dwordx4 v[8:9], off
	v_lshl_add_u64 v[8:9], v[12:13], 0, s[54:55]
	s_mov_b32 m0, s26
	s_add_u32 s10, s8, 0x100080
	global_load_lds_dwordx4 v[8:9], off
	v_lshl_add_u64 v[8:9], v[14:15], 0, s[54:55]
	s_mov_b32 m0, s27
	s_addc_u32 s11, s9, 0
	global_load_lds_dwordx4 v[8:9], off
	s_add_i32 m0, s22, 0x1c000
	s_nop 0
	global_load_lds_dwordx4 v178, s[10:11]
	s_add_i32 m0, s22, 0x1e000
	v_lshlrev_b32_e32 v3, 2, v3
	global_load_lds_dwordx4 v128, s[10:11]
	v_lshl_or_b32 v7, v7, 6, v17
	v_and_b32_e32 v3, 32, v3
	v_bitop3_b32 v140, v7, s19, v3 bitop3:0xde
	v_lshlrev_b32_e32 v3, 16, v0
	v_and_b32_e32 v3, 0xfffe0000, v3
	v_readlane_b32 s10, v253, 49
	v_lshl_add_u32 v1, v1, 13, v3
	v_and_b32_e32 v0, 1, v0
	s_add_u32 s10, s88, s10
	v_lshl_or_b32 v0, v0, 6, v1
	s_addc_u32 s11, s89, 0
	v_lshl_add_u32 v0, v2, 1, v0
	v_mov_b32_e32 v1, v179
	v_lshl_add_u64 v[134:135], s[10:11], 0, v[0:1]
	v_lshlrev_b32_e32 v0, 16, v4
	v_and_b32_e32 v0, 0xfffe0000, v0
	v_lshl_add_u32 v0, v5, 13, v0
	v_and_b32_e32 v1, 1, v4
	v_lshlrev_b32_e32 v18, 2, v138
	v_lshl_or_b32 v0, v1, 6, v0
	v_and_b32_e32 v18, 32, v18
	s_waitcnt vmcnt(6)
	v_lshl_add_u32 v0, v6, 1, v0
	v_mov_b32_e32 v1, v179
	v_bitop3_b32 v16, v16, s18, v18 bitop3:0xde
	v_lshl_add_u64 v[136:137], s[10:11], 0, v[0:1]
	v_mov_b32_e32 v0, 0
	s_mov_b32 s28, -2
	s_mov_b64 s[10:11], 0xb400080
	v_add_u32_e32 v141, 0, v16
	v_mov_b32_e32 v1, 0
	v_mov_b64_e32 v[2:3], 0
	v_mov_b64_e32 v[4:5], 0
	v_mov_b64_e32 v[6:7], 0
	v_mov_b64_e32 v[8:9], 0
	v_mov_b64_e32 v[10:11], 0
	v_mov_b64_e32 v[12:13], 0
	v_mov_b64_e32 v[14:15], 0
	v_mov_b64_e32 v[16:17], 0
	v_mov_b64_e32 v[18:19], 0
	v_mov_b64_e32 v[20:21], 0
	v_mov_b64_e32 v[22:23], 0
	v_mov_b64_e32 v[24:25], 0
	v_mov_b64_e32 v[26:27], 0
	v_mov_b64_e32 v[28:29], 0
	v_mov_b64_e32 v[30:31], 0
	v_mov_b64_e32 v[32:33], 0
	v_mov_b64_e32 v[34:35], 0
	v_mov_b64_e32 v[36:37], 0
	v_mov_b64_e32 v[38:39], 0
	v_mov_b64_e32 v[40:41], 0
	v_mov_b64_e32 v[42:43], 0
	v_mov_b64_e32 v[44:45], 0
	v_mov_b64_e32 v[46:47], 0
	v_mov_b64_e32 v[48:49], 0
	v_mov_b64_e32 v[50:51], 0
	v_mov_b64_e32 v[52:53], 0
	v_mov_b64_e32 v[54:55], 0
	v_mov_b64_e32 v[56:57], 0
	v_mov_b64_e32 v[58:59], 0
	v_mov_b64_e32 v[60:61], 0
	v_mov_b64_e32 v[62:63], 0
	v_mov_b64_e32 v[64:65], 0
	v_mov_b64_e32 v[66:67], 0
	v_mov_b64_e32 v[68:69], 0
	v_mov_b64_e32 v[70:71], 0
	v_mov_b64_e32 v[72:73], 0
	v_mov_b64_e32 v[74:75], 0
	v_mov_b64_e32 v[76:77], 0
	v_mov_b64_e32 v[78:79], 0
	v_mov_b64_e32 v[80:81], 0
	v_mov_b64_e32 v[82:83], 0
	v_mov_b64_e32 v[84:85], 0
	v_mov_b64_e32 v[86:87], 0
	v_mov_b64_e32 v[88:89], 0
	v_mov_b64_e32 v[90:91], 0
	v_mov_b64_e32 v[92:93], 0
	v_mov_b64_e32 v[94:95], 0
	v_mov_b64_e32 v[96:97], 0
	v_mov_b64_e32 v[98:99], 0
	v_mov_b64_e32 v[100:101], 0
	v_mov_b64_e32 v[102:103], 0
	v_mov_b64_e32 v[104:105], 0
	v_mov_b64_e32 v[106:107], 0
	v_mov_b64_e32 v[108:109], 0
	v_mov_b64_e32 v[110:111], 0
	v_mov_b64_e32 v[112:113], 0
	v_mov_b64_e32 v[114:115], 0
	v_mov_b64_e32 v[116:117], 0
	v_mov_b64_e32 v[118:119], 0
	v_mov_b64_e32 v[120:121], 0
	v_mov_b64_e32 v[122:123], 0
	v_mov_b64_e32 v[124:125], 0
	v_mov_b64_e32 v[126:127], 0
	s_barrier
.LBB0_935:
	s_add_u32 s12, s10, 0xf4c00080
	s_addc_u32 s13, s11, -1
	s_cmp_lg_u32 s28, 60
	s_cselect_b32 s12, s12, 0
	s_cselect_b32 s13, s13, 0
	s_add_u32 s14, s6, s12
	s_addc_u32 s15, s7, s13
	s_add_i32 s29, 0, 0x10000
	v_add_u32_e32 v150, s29, v140
	ds_read_b128 v[142:145], v150
	ds_read_b128 v[146:149], v150 offset:1024
	ds_read_b128 v[154:157], v150 offset:2048
	ds_read_b128 v[158:161], v150 offset:3072
	s_add_u32 s12, s8, s12
	s_addc_u32 s13, s9, s13
	v_lshl_add_u64 v[150:151], v[136:137], 0, s[10:11]
	s_add_i32 m0, s22, 0xc000
	ds_read_b128 v[162:165], v141
	ds_read_b128 v[166:169], v141 offset:1024
	ds_read_b128 v[170:173], v141 offset:2048
	ds_read_b128 v[174:177], v141 offset:3072
	ds_read_b128 v[180:183], v141 offset:4096
	ds_read_b128 v[184:187], v141 offset:5120
	ds_read_b128 v[188:191], v141 offset:6144
	ds_read_b128 v[192:195], v141 offset:7168
	global_load_lds_dwordx4 v[150:151], off
	v_lshl_add_u64 v[150:151], v[134:135], 0, s[10:11]
	s_add_i32 m0, s22, 0xe000
	s_nop 0
	global_load_lds_dwordx4 v[150:151], off
	s_waitcnt lgkmcnt(8)
	s_barrier
	s_waitcnt lgkmcnt(0)
	v_mfma_f32_16x16x32_bf16 v[124:127], v[142:145], v[162:165], v[124:127]
	v_mfma_f32_16x16x32_bf16 v[120:123], v[154:157], v[162:165], v[120:123]
	v_mfma_f32_16x16x32_bf16 v[116:119], v[142:145], v[170:173], v[116:119]
	v_mfma_f32_16x16x32_bf16 v[108:111], v[154:157], v[170:173], v[108:111]
	v_mfma_f32_16x16x32_bf16 v[100:103], v[142:145], v[180:183], v[100:103]
	v_mfma_f32_16x16x32_bf16 v[92:95], v[154:157], v[180:183], v[92:95]
	v_mfma_f32_16x16x32_bf16 v[84:87], v[142:145], v[188:191], v[84:87]
	v_mfma_f32_16x16x32_bf16 v[76:79], v[154:157], v[188:191], v[76:79]
	v_mfma_f32_16x16x32_bf16 v[124:127], v[146:149], v[166:169], v[124:127]
	v_mfma_f32_16x16x32_bf16 v[120:123], v[158:161], v[166:169], v[120:123]
	v_mfma_f32_16x16x32_bf16 v[116:119], v[146:149], v[174:177], v[116:119]
	v_mfma_f32_16x16x32_bf16 v[108:111], v[158:161], v[174:177], v[108:111]
	v_mfma_f32_16x16x32_bf16 v[100:103], v[146:149], v[184:187], v[100:103]
	v_mfma_f32_16x16x32_bf16 v[92:95], v[158:161], v[184:187], v[92:95]
	v_mfma_f32_16x16x32_bf16 v[84:87], v[146:149], v[192:195], v[84:87]
	v_mfma_f32_16x16x32_bf16 v[76:79], v[158:161], v[192:195], v[76:79]
	s_barrier
	s_add_i32 s35, 0, 0x14000
	v_add_u32_e32 v150, s35, v140
	s_add_i32 s29, s29, s16
	ds_read_b128 v[196:199], v150
	ds_read_b128 v[224:227], v150 offset:1024
	ds_read_b128 v[228:231], v150 offset:2048
	ds_read_b128 v[232:235], v150 offset:3072
	s_mov_b32 m0, s29
	s_nop 0
	global_load_lds_dwordx4 v178, s[12:13]
	s_add_i32 m0, s29, 0x2000
	s_nop 0
	global_load_lds_dwordx4 v128, s[12:13]
	s_barrier
	s_waitcnt lgkmcnt(0)
	v_mfma_f32_16x16x32_bf16 v[112:115], v[196:199], v[162:165], v[112:115]
	v_mfma_f32_16x16x32_bf16 v[104:107], v[228:231], v[162:165], v[104:107]
	v_mfma_f32_16x16x32_bf16 v[96:99], v[196:199], v[170:173], v[96:99]
	v_mfma_f32_16x16x32_bf16 v[88:91], v[228:231], v[170:173], v[88:91]
	v_mfma_f32_16x16x32_bf16 v[80:83], v[196:199], v[180:183], v[80:83]
	v_mfma_f32_16x16x32_bf16 v[72:75], v[228:231], v[180:183], v[72:75]
	v_mfma_f32_16x16x32_bf16 v[68:71], v[196:199], v[188:191], v[68:71]
	v_mfma_f32_16x16x32_bf16 v[64:67], v[228:231], v[188:191], v[64:67]
	v_mfma_f32_16x16x32_bf16 v[112:115], v[224:227], v[166:169], v[112:115]
	v_mfma_f32_16x16x32_bf16 v[104:107], v[232:235], v[166:169], v[104:107]
	v_mfma_f32_16x16x32_bf16 v[96:99], v[224:227], v[174:177], v[96:99]
	v_mfma_f32_16x16x32_bf16 v[88:91], v[232:235], v[174:177], v[88:91]
	v_mfma_f32_16x16x32_bf16 v[80:83], v[224:227], v[184:187], v[80:83]
	v_mfma_f32_16x16x32_bf16 v[72:75], v[232:235], v[184:187], v[72:75]
	v_mfma_f32_16x16x32_bf16 v[68:71], v[224:227], v[192:195], v[68:71]
	v_mfma_f32_16x16x32_bf16 v[64:67], v[232:235], v[192:195], v[64:67]
	s_mov_b32 m0, s22
	s_mov_b64 s[100:101], s[14:15]
	s_barrier
	ds_read_b128 v[162:165], v141 offset:16384
	ds_read_b128 v[166:169], v141 offset:17408
	ds_read_b128 v[170:173], v141 offset:18432
	ds_read_b128 v[174:177], v141 offset:19456
	ds_read_b128 v[180:183], v141 offset:20480
	ds_read_b128 v[184:187], v141 offset:21504
	ds_read_b128 v[188:191], v141 offset:22528
	ds_read_b128 v[192:195], v141 offset:23552
	global_load_lds_dwordx4 v132, s[14:15]
	s_mov_b64 s[100:101], s[14:15]
	s_mov_b32 m0, s23
	s_nop 0
	global_load_lds_dwordx4 v130, s[14:15]
	s_barrier
	s_waitcnt lgkmcnt(0)
	v_mfma_f32_16x16x32_bf16 v[60:63], v[142:145], v[162:165], v[60:63]
	v_mfma_f32_16x16x32_bf16 v[56:59], v[154:157], v[162:165], v[56:59]
	v_mfma_f32_16x16x32_bf16 v[52:55], v[142:145], v[170:173], v[52:55]
	v_mfma_f32_16x16x32_bf16 v[44:47], v[154:157], v[170:173], v[44:47]
	v_mfma_f32_16x16x32_bf16 v[36:39], v[142:145], v[180:183], v[36:39]
	v_mfma_f32_16x16x32_bf16 v[28:31], v[154:157], v[180:183], v[28:31]
	v_mfma_f32_16x16x32_bf16 v[20:23], v[142:145], v[188:191], v[20:23]
	v_mfma_f32_16x16x32_bf16 v[12:15], v[154:157], v[188:191], v[12:15]
	v_mfma_f32_16x16x32_bf16 v[60:63], v[146:149], v[166:169], v[60:63]
	v_mfma_f32_16x16x32_bf16 v[56:59], v[158:161], v[166:169], v[56:59]
	v_mfma_f32_16x16x32_bf16 v[52:55], v[146:149], v[174:177], v[52:55]
	v_mfma_f32_16x16x32_bf16 v[44:47], v[158:161], v[174:177], v[44:47]
	v_mfma_f32_16x16x32_bf16 v[36:39], v[146:149], v[184:187], v[36:39]
	v_mfma_f32_16x16x32_bf16 v[28:31], v[158:161], v[184:187], v[28:31]
	v_mfma_f32_16x16x32_bf16 v[20:23], v[146:149], v[192:195], v[20:23]
	v_mfma_f32_16x16x32_bf16 v[12:15], v[158:161], v[192:195], v[12:15]
	s_barrier
	s_add_u32 s30, s12, 0x100000
	s_addc_u32 s31, s13, 0
	s_add_i32 s29, s35, s16
	s_mov_b32 m0, s29
	s_nop 0
	global_load_lds_dwordx4 v178, s[30:31]
	s_add_i32 m0, s29, 0x2000
	s_nop 0
	global_load_lds_dwordx4 v128, s[30:31]
	s_waitcnt vmcnt(6)
	s_barrier
	v_mfma_f32_16x16x32_bf16 v[48:51], v[196:199], v[162:165], v[48:51]
	v_mfma_f32_16x16x32_bf16 v[40:43], v[228:231], v[162:165], v[40:43]
	v_mfma_f32_16x16x32_bf16 v[32:35], v[196:199], v[170:173], v[32:35]
	v_mfma_f32_16x16x32_bf16 v[24:27], v[228:231], v[170:173], v[24:27]
	v_mfma_f32_16x16x32_bf16 v[16:19], v[196:199], v[180:183], v[16:19]
	v_mfma_f32_16x16x32_bf16 v[8:11], v[228:231], v[180:183], v[8:11]
	v_mfma_f32_16x16x32_bf16 v[4:7], v[196:199], v[188:191], v[4:7]
	v_mfma_f32_16x16x32_bf16 v[0:3], v[228:231], v[188:191], v[0:3]
	v_mfma_f32_16x16x32_bf16 v[48:51], v[224:227], v[166:169], v[48:51]
	v_mfma_f32_16x16x32_bf16 v[40:43], v[232:235], v[166:169], v[40:43]
	v_mfma_f32_16x16x32_bf16 v[32:35], v[224:227], v[174:177], v[32:35]
	v_mfma_f32_16x16x32_bf16 v[24:27], v[232:235], v[174:177], v[24:27]
	v_mfma_f32_16x16x32_bf16 v[16:19], v[224:227], v[184:187], v[16:19]
	v_mfma_f32_16x16x32_bf16 v[8:11], v[232:235], v[184:187], v[8:11]
	v_mfma_f32_16x16x32_bf16 v[4:7], v[224:227], v[192:195], v[4:7]
	v_mfma_f32_16x16x32_bf16 v[0:3], v[232:235], v[192:195], v[0:3]
	s_add_i32 s29, 0, 0x18000
	v_add_u32_e32 v153, s29, v140
	s_barrier
	ds_read_b128 v[142:145], v153
	ds_read_b128 v[146:149], v153 offset:1024
	ds_read_b128 v[154:157], v153 offset:2048
	ds_read_b128 v[158:161], v153 offset:3072
	s_add_u32 s14, s14, 0x100000
	s_addc_u32 s15, s15, 0
	s_mov_b32 m0, s24
	ds_read_b128 v[162:165], v141 offset:32768
	ds_read_b128 v[166:169], v141 offset:33792
	ds_read_b128 v[170:173], v141 offset:34816
	ds_read_b128 v[174:177], v141 offset:35840
	ds_read_b128 v[180:183], v141 offset:36864
	ds_read_b128 v[184:187], v141 offset:37888
	ds_read_b128 v[188:191], v141 offset:38912
	ds_read_b128 v[192:195], v141 offset:39936
	global_load_lds_dwordx4 v132, s[14:15]
	s_mov_b32 m0, s25
	s_nop 0
	global_load_lds_dwordx4 v130, s[14:15]
	s_waitcnt lgkmcnt(8)
	s_barrier
	s_waitcnt lgkmcnt(0)
	v_mfma_f32_16x16x32_bf16 v[124:127], v[142:145], v[162:165], v[124:127]
	v_mfma_f32_16x16x32_bf16 v[120:123], v[154:157], v[162:165], v[120:123]
	v_mfma_f32_16x16x32_bf16 v[116:119], v[142:145], v[170:173], v[116:119]
	v_mfma_f32_16x16x32_bf16 v[108:111], v[154:157], v[170:173], v[108:111]
	v_mfma_f32_16x16x32_bf16 v[100:103], v[142:145], v[180:183], v[100:103]
	v_mfma_f32_16x16x32_bf16 v[92:95], v[154:157], v[180:183], v[92:95]
	v_mfma_f32_16x16x32_bf16 v[84:87], v[142:145], v[188:191], v[84:87]
	v_mfma_f32_16x16x32_bf16 v[76:79], v[154:157], v[188:191], v[76:79]
	v_mfma_f32_16x16x32_bf16 v[124:127], v[146:149], v[166:169], v[124:127]
	v_mfma_f32_16x16x32_bf16 v[120:123], v[158:161], v[166:169], v[120:123]
	v_mfma_f32_16x16x32_bf16 v[116:119], v[146:149], v[174:177], v[116:119]
	v_mfma_f32_16x16x32_bf16 v[108:111], v[158:161], v[174:177], v[108:111]
	v_mfma_f32_16x16x32_bf16 v[100:103], v[146:149], v[184:187], v[100:103]
	v_mfma_f32_16x16x32_bf16 v[92:95], v[158:161], v[184:187], v[92:95]
	v_mfma_f32_16x16x32_bf16 v[84:87], v[146:149], v[192:195], v[84:87]
	v_mfma_f32_16x16x32_bf16 v[76:79], v[158:161], v[192:195], v[76:79]
	s_barrier
	s_add_i32 s14, 0, 0x1c000
	s_add_i32 s15, s29, s16
	v_add_u32_e32 v153, s14, v140
	s_add_i32 m0, s15, 0xffffff80
	ds_read_b128 v[196:199], v153
	ds_read_b128 v[224:227], v153 offset:1024
	ds_read_b128 v[228:231], v153 offset:2048
	ds_read_b128 v[232:235], v153 offset:3072
	global_load_lds_dwordx4 v178, s[12:13] offset:128
	s_add_i32 m0, s15, 0x1f80
	s_nop 0
	global_load_lds_dwordx4 v128, s[12:13] offset:128
	s_barrier
	s_waitcnt lgkmcnt(0)
	v_mfma_f32_16x16x32_bf16 v[112:115], v[196:199], v[162:165], v[112:115]
	v_mfma_f32_16x16x32_bf16 v[104:107], v[228:231], v[162:165], v[104:107]
	v_mfma_f32_16x16x32_bf16 v[96:99], v[196:199], v[170:173], v[96:99]
	v_mfma_f32_16x16x32_bf16 v[88:91], v[228:231], v[170:173], v[88:91]
	v_mfma_f32_16x16x32_bf16 v[80:83], v[196:199], v[180:183], v[80:83]
	v_mfma_f32_16x16x32_bf16 v[72:75], v[228:231], v[180:183], v[72:75]
	v_mfma_f32_16x16x32_bf16 v[68:71], v[196:199], v[188:191], v[68:71]
	v_mfma_f32_16x16x32_bf16 v[64:67], v[228:231], v[188:191], v[64:67]
	v_mfma_f32_16x16x32_bf16 v[112:115], v[224:227], v[166:169], v[112:115]
	v_mfma_f32_16x16x32_bf16 v[104:107], v[232:235], v[166:169], v[104:107]
	v_mfma_f32_16x16x32_bf16 v[96:99], v[224:227], v[174:177], v[96:99]
	v_mfma_f32_16x16x32_bf16 v[88:91], v[232:235], v[174:177], v[88:91]
	v_mfma_f32_16x16x32_bf16 v[80:83], v[224:227], v[184:187], v[80:83]
	v_mfma_f32_16x16x32_bf16 v[72:75], v[232:235], v[184:187], v[72:75]
	v_mfma_f32_16x16x32_bf16 v[68:71], v[224:227], v[192:195], v[68:71]
	v_mfma_f32_16x16x32_bf16 v[64:67], v[232:235], v[192:195], v[64:67]
	s_add_i32 m0, s26, 0xffffff80
	s_barrier
	ds_read_b128 v[162:165], v141 offset:49152
	ds_read_b128 v[166:169], v141 offset:50176
	ds_read_b128 v[170:173], v141 offset:51200
	ds_read_b128 v[174:177], v141 offset:52224
	ds_read_b128 v[180:183], v141 offset:53248
	ds_read_b128 v[184:187], v141 offset:54272
	ds_read_b128 v[188:191], v141 offset:55296
	ds_read_b128 v[192:195], v141 offset:56320
	global_load_lds_dwordx4 v132, s[100:101] offset:128
	s_add_i32 m0, s27, 0xffffff80
	s_nop 0
	global_load_lds_dwordx4 v130, s[100:101] offset:128
	s_barrier
	s_waitcnt lgkmcnt(0)
	v_mfma_f32_16x16x32_bf16 v[60:63], v[142:145], v[162:165], v[60:63]
	v_mfma_f32_16x16x32_bf16 v[56:59], v[154:157], v[162:165], v[56:59]
	v_mfma_f32_16x16x32_bf16 v[52:55], v[142:145], v[170:173], v[52:55]
	v_mfma_f32_16x16x32_bf16 v[44:47], v[154:157], v[170:173], v[44:47]
	v_mfma_f32_16x16x32_bf16 v[36:39], v[142:145], v[180:183], v[36:39]
	v_mfma_f32_16x16x32_bf16 v[28:31], v[154:157], v[180:183], v[28:31]
	v_mfma_f32_16x16x32_bf16 v[20:23], v[142:145], v[188:191], v[20:23]
	v_mfma_f32_16x16x32_bf16 v[12:15], v[154:157], v[188:191], v[12:15]
	v_mfma_f32_16x16x32_bf16 v[60:63], v[146:149], v[166:169], v[60:63]
	v_mfma_f32_16x16x32_bf16 v[56:59], v[158:161], v[166:169], v[56:59]
	v_mfma_f32_16x16x32_bf16 v[52:55], v[146:149], v[174:177], v[52:55]
	v_mfma_f32_16x16x32_bf16 v[44:47], v[158:161], v[174:177], v[44:47]
	v_mfma_f32_16x16x32_bf16 v[36:39], v[146:149], v[184:187], v[36:39]
	v_mfma_f32_16x16x32_bf16 v[28:31], v[158:161], v[184:187], v[28:31]
	v_mfma_f32_16x16x32_bf16 v[20:23], v[146:149], v[192:195], v[20:23]
	v_mfma_f32_16x16x32_bf16 v[12:15], v[158:161], v[192:195], v[12:15]
	s_barrier
	s_add_u32 s12, s12, 0x100080
	s_addc_u32 s13, s13, 0
	s_add_i32 s14, s14, s16
	s_mov_b32 m0, s14
	s_nop 0
	global_load_lds_dwordx4 v178, s[12:13]
	s_add_i32 m0, s14, 0x2000
	s_nop 0
	global_load_lds_dwordx4 v128, s[12:13]
	s_waitcnt vmcnt(6)
	s_barrier
	v_mfma_f32_16x16x32_bf16 v[48:51], v[196:199], v[162:165], v[48:51]
	v_mfma_f32_16x16x32_bf16 v[40:43], v[228:231], v[162:165], v[40:43]
	v_mfma_f32_16x16x32_bf16 v[32:35], v[196:199], v[170:173], v[32:35]
	v_mfma_f32_16x16x32_bf16 v[24:27], v[228:231], v[170:173], v[24:27]
	v_mfma_f32_16x16x32_bf16 v[16:19], v[196:199], v[180:183], v[16:19]
	v_mfma_f32_16x16x32_bf16 v[8:11], v[228:231], v[180:183], v[8:11]
	v_mfma_f32_16x16x32_bf16 v[4:7], v[196:199], v[188:191], v[4:7]
	v_mfma_f32_16x16x32_bf16 v[0:3], v[228:231], v[188:191], v[0:3]
	v_mfma_f32_16x16x32_bf16 v[48:51], v[224:227], v[166:169], v[48:51]
	v_mfma_f32_16x16x32_bf16 v[40:43], v[232:235], v[166:169], v[40:43]
	v_mfma_f32_16x16x32_bf16 v[32:35], v[224:227], v[174:177], v[32:35]
	v_mfma_f32_16x16x32_bf16 v[24:27], v[232:235], v[174:177], v[24:27]
	v_mfma_f32_16x16x32_bf16 v[16:19], v[224:227], v[184:187], v[16:19]
	v_mfma_f32_16x16x32_bf16 v[8:11], v[232:235], v[184:187], v[8:11]
	v_mfma_f32_16x16x32_bf16 v[4:7], v[224:227], v[192:195], v[4:7]
	v_mfma_f32_16x16x32_bf16 v[0:3], v[232:235], v[192:195], v[0:3]
	s_add_i32 s28, s28, 2
	s_add_u32 s10, s10, 0x100
	s_addc_u32 s11, s11, 0
	s_cmp_gt_u32 s28, 61
	s_barrier
	s_cbranch_scc0 .LBB0_935
	v_readlane_b32 s6, v253, 51
	s_or_b32 s6, s17, s6
	v_cvt_pk_bf16_f32 v124, v124, v125
	v_cvt_pk_bf16_f32 v125, v126, v127
	v_cvt_pk_bf16_f32 v126, v120, v121
	v_cvt_pk_bf16_f32 v127, v122, v123
	s_nop 0
	v_or_b32_e32 v130, s6, v139
	v_readlane_b32 s6, v253, 44
	v_lshlrev_b32_e32 v178, 1, v130
	s_nop 0
	v_add_u32_e32 v131, s6, v138
	v_add_u32_e32 v128, 0x1000, v131
	v_ashrrev_i32_e32 v129, 31, v128
	v_lshlrev_b64 v[128:129], 12, v[128:129]
	v_lshl_add_u64 v[128:129], s[4:5], 0, v[128:129]
	v_lshl_add_u64 v[128:129], v[128:129], 0, v[178:179]
	global_store_dwordx4 v[128:129], v[124:127], off
	v_cvt_pk_bf16_f32 v112, v112, v113
	v_cvt_pk_bf16_f32 v113, v114, v115
	v_cvt_pk_bf16_f32 v114, v104, v105
	v_add_u32_e32 v104, 0x1010, v131
	v_ashrrev_i32_e32 v105, 31, v104
	v_lshlrev_b64 v[104:105], 12, v[104:105]
	v_lshl_add_u64 v[104:105], s[4:5], 0, v[104:105]
	v_cvt_pk_bf16_f32 v115, v106, v107
	global_store_dwordx4 v[128:129], v[112:115], off offset:256
	v_readlane_b32 s6, v255, 8
	s_nop 0
	v_lshl_add_u64 v[112:113], v[104:105], 0, v[178:179]
	v_cvt_pk_bf16_f32 v104, v116, v117
	v_cvt_pk_bf16_f32 v105, v118, v119
	v_cvt_pk_bf16_f32 v106, v108, v109
	v_cvt_pk_bf16_f32 v107, v110, v111
	global_store_dwordx4 v[112:113], v[104:107], off
	v_cvt_pk_bf16_f32 v96, v96, v97
	v_cvt_pk_bf16_f32 v97, v98, v99
	v_cvt_pk_bf16_f32 v98, v88, v89
	v_add_u32_e32 v88, 0x1020, v131
	v_ashrrev_i32_e32 v89, 31, v88
	v_lshlrev_b64 v[88:89], 12, v[88:89]
	v_lshl_add_u64 v[88:89], s[4:5], 0, v[88:89]
	v_cvt_pk_bf16_f32 v99, v90, v91
	global_store_dwordx4 v[112:113], v[96:99], off offset:256
	s_nop 1
	v_lshl_add_u64 v[96:97], v[88:89], 0, v[178:179]
	v_cvt_pk_bf16_f32 v88, v100, v101
	v_cvt_pk_bf16_f32 v89, v102, v103
	v_cvt_pk_bf16_f32 v90, v92, v93
	v_cvt_pk_bf16_f32 v91, v94, v95
	global_store_dwordx4 v[96:97], v[88:91], off
	v_cvt_pk_bf16_f32 v80, v80, v81
	v_cvt_pk_bf16_f32 v81, v82, v83
	v_cvt_pk_bf16_f32 v82, v72, v73
	v_add_u32_e32 v72, 0x1030, v131
	v_ashrrev_i32_e32 v73, 31, v72
	v_lshlrev_b64 v[72:73], 12, v[72:73]
	v_lshl_add_u64 v[72:73], s[4:5], 0, v[72:73]
	v_cvt_pk_bf16_f32 v83, v74, v75
	global_store_dwordx4 v[96:97], v[80:83], off offset:256
	s_nop 1
	v_lshl_add_u64 v[80:81], v[72:73], 0, v[178:179]
	v_cvt_pk_bf16_f32 v72, v84, v85
	v_cvt_pk_bf16_f32 v73, v86, v87
	v_cvt_pk_bf16_f32 v74, v76, v77
	v_cvt_pk_bf16_f32 v75, v78, v79
	global_store_dwordx4 v[80:81], v[72:75], off
	v_cvt_pk_bf16_f32 v68, v68, v69
	v_cvt_pk_bf16_f32 v69, v70, v71
	v_cvt_pk_bf16_f32 v70, v64, v65
	v_add_u32_e32 v64, 0x1080, v131
	v_ashrrev_i32_e32 v65, 31, v64
	v_lshlrev_b64 v[64:65], 12, v[64:65]
	v_lshl_add_u64 v[64:65], s[4:5], 0, v[64:65]
	v_lshl_add_u64 v[64:65], v[64:65], 0, v[178:179]
	v_cvt_pk_bf16_f32 v71, v66, v67
	global_store_dwordx4 v[80:81], v[68:71], off offset:256
	v_cvt_pk_bf16_f32 v60, v60, v61
	v_cvt_pk_bf16_f32 v61, v62, v63
	v_cvt_pk_bf16_f32 v62, v56, v57
	v_cvt_pk_bf16_f32 v63, v58, v59
	global_store_dwordx4 v[64:65], v[60:63], off
	v_cvt_pk_bf16_f32 v48, v48, v49
	v_cvt_pk_bf16_f32 v49, v50, v51
	v_cvt_pk_bf16_f32 v50, v40, v41
	v_add_u32_e32 v40, 0x1090, v131
	v_ashrrev_i32_e32 v41, 31, v40
	v_lshlrev_b64 v[40:41], 12, v[40:41]
	v_lshl_add_u64 v[40:41], s[4:5], 0, v[40:41]
	v_cvt_pk_bf16_f32 v51, v42, v43
	global_store_dwordx4 v[64:65], v[48:51], off offset:256
	s_nop 1
	v_lshl_add_u64 v[48:49], v[40:41], 0, v[178:179]
	v_cvt_pk_bf16_f32 v40, v52, v53
	v_cvt_pk_bf16_f32 v41, v54, v55
	v_cvt_pk_bf16_f32 v42, v44, v45
	v_cvt_pk_bf16_f32 v43, v46, v47
	global_store_dwordx4 v[48:49], v[40:43], off
	v_cvt_pk_bf16_f32 v32, v32, v33
	v_cvt_pk_bf16_f32 v33, v34, v35
	v_cvt_pk_bf16_f32 v34, v24, v25
	v_add_u32_e32 v24, 0x10a0, v131
	v_ashrrev_i32_e32 v25, 31, v24
	v_lshlrev_b64 v[24:25], 12, v[24:25]
	v_lshl_add_u64 v[24:25], s[4:5], 0, v[24:25]
	v_cvt_pk_bf16_f32 v35, v26, v27
	global_store_dwordx4 v[48:49], v[32:35], off offset:256
	s_nop 1
	v_lshl_add_u64 v[32:33], v[24:25], 0, v[178:179]
	v_cvt_pk_bf16_f32 v24, v36, v37
	v_cvt_pk_bf16_f32 v25, v38, v39
	v_cvt_pk_bf16_f32 v26, v28, v29
	v_cvt_pk_bf16_f32 v27, v30, v31
	global_store_dwordx4 v[32:33], v[24:27], off
	v_cvt_pk_bf16_f32 v16, v16, v17
	v_cvt_pk_bf16_f32 v17, v18, v19
	v_cvt_pk_bf16_f32 v18, v8, v9
	v_add_u32_e32 v8, 0x10b0, v131
	v_ashrrev_i32_e32 v9, 31, v8
	v_lshlrev_b64 v[8:9], 12, v[8:9]
	v_lshl_add_u64 v[8:9], s[4:5], 0, v[8:9]
	v_cvt_pk_bf16_f32 v19, v10, v11
	global_store_dwordx4 v[32:33], v[16:19], off offset:256
	s_nop 1
	v_lshl_add_u64 v[16:17], v[8:9], 0, v[178:179]
	v_cvt_pk_bf16_f32 v8, v20, v21
	v_cvt_pk_bf16_f32 v9, v22, v23
	v_cvt_pk_bf16_f32 v10, v12, v13
	v_cvt_pk_bf16_f32 v11, v14, v15
	global_store_dwordx4 v[16:17], v[8:11], off
	v_cvt_pk_bf16_f32 v4, v4, v5
	v_cvt_pk_bf16_f32 v5, v6, v7
	v_cvt_pk_bf16_f32 v6, v0, v1
	v_cvt_pk_bf16_f32 v7, v2, v3
	global_store_dwordx4 v[16:17], v[4:7], off offset:256
	s_waitcnt vmcnt(0)
	s_cmp_lt_u32 s6, 4
	s_cbranch_scc0 .LBB0_938
	s_barrier

.LBB0_942:
	v_lshl_add_u64 v[8:9], s[8:9], 0, v[178:179]
	v_and_b32_e32 v7, 15, v3
	v_lshrrev_b32_e32 v12, 1, v3
	v_or_b32_e32 v138, s20, v7
	v_and_b32_e32 v139, 24, v12
	s_add_i32 m0, s22, 0x18000
	v_lshl_add_u64 v[8:9], v[8:9], 0, s[54:55]
	v_mov_b32_e32 v129, v179
	v_lshlrev_b32_e32 v12, 6, v138
	v_lshlrev_b32_e32 v13, 1, v139
	s_movk_i32 s10, 0x3c0
	v_lshlrev_b32_e32 v14, 2, v138
	s_waitcnt vmcnt(4)
	s_barrier
	global_load_lds_dwordx4 v[8:9], off
	s_add_i32 m0, s22, 0x1a000
	v_lshl_add_u64 v[10:11], s[8:9], 0, v[128:129]
	v_and_or_b32 v12, v12, s10, v13
	v_and_b32_e32 v14, 32, v14
	v_lshlrev_b32_e32 v3, 2, v3
	s_add_u32 s10, s88, 0xc300080
	v_mov_b32_e32 v133, v179
	v_bitop3_b32 v12, v12, s18, v14 bitop3:0xde
	v_lshl_or_b32 v7, v7, 6, v13
	v_and_b32_e32 v3, 32, v3
	v_lshl_add_u64 v[8:9], v[10:11], 0, s[54:55]
	s_addc_u32 s11, s89, 0
	s_add_i32 s18, s22, 0x8000
	v_mov_b32_e32 v131, v179
	v_bitop3_b32 v140, v7, s19, v3 bitop3:0xde
	global_load_lds_dwordx4 v[8:9], off
	s_mov_b32 m0, s18
	s_add_i32 s19, s22, 0xa000
	global_load_lds_dwordx4 v132, s[10:11]
	v_lshl_add_u64 v[8:9], s[10:11], 0, v[130:131]
	s_add_u32 s10, s8, 0x20080
	s_mov_b32 m0, s19
	s_addc_u32 s11, s9, 0
	global_load_lds_dwordx4 v[8:9], off
	s_add_i32 m0, s22, 0x1c000
	s_nop 0
	global_load_lds_dwordx4 v178, s[10:11]
	s_add_i32 m0, s22, 0x1e000
	v_lshlrev_b32_e32 v3, 13, v0
	global_load_lds_dwordx4 v128, s[10:11]
	v_and_b32_e32 v3, 0xffffc000, v3
	v_lshl_add_u32 v1, v1, 10, v3
	v_and_b32_e32 v0, 1, v0
	v_lshl_or_b32 v0, v0, 6, v1
	v_lshl_add_u32 v0, v2, 1, v0
	v_mov_b32_e32 v1, v179
	v_lshl_add_u64 v[134:135], s[88:89], 0, v[0:1]
	v_lshlrev_b32_e32 v0, 13, v4
	v_and_b32_e32 v0, 0xffffc000, v0
	v_lshl_add_u32 v0, v5, 10, v0
	v_and_b32_e32 v1, 1, v4
	v_lshl_or_b32 v0, v1, 6, v0
	s_waitcnt vmcnt(6)
	v_lshl_add_u32 v0, v6, 1, v0
	v_mov_b32_e32 v1, v179
	v_lshl_add_u64 v[136:137], s[88:89], 0, v[0:1]
	v_mov_b32_e32 v0, 0
	s_mov_b32 s20, -2
	s_mov_b64 s[10:11], 0xc320080
	v_add_u32_e32 v141, 0, v12
	v_mov_b32_e32 v1, 0
	v_mov_b64_e32 v[2:3], 0
	v_mov_b64_e32 v[4:5], 0
	v_mov_b64_e32 v[6:7], 0
	v_mov_b64_e32 v[8:9], 0
	v_mov_b64_e32 v[10:11], 0
	v_mov_b64_e32 v[12:13], 0
	v_mov_b64_e32 v[14:15], 0
	v_mov_b64_e32 v[16:17], 0
	v_mov_b64_e32 v[18:19], 0
	v_mov_b64_e32 v[20:21], 0
	v_mov_b64_e32 v[22:23], 0
	v_mov_b64_e32 v[24:25], 0
	v_mov_b64_e32 v[26:27], 0
	v_mov_b64_e32 v[28:29], 0
	v_mov_b64_e32 v[30:31], 0
	v_mov_b64_e32 v[32:33], 0
	v_mov_b64_e32 v[34:35], 0
	v_mov_b64_e32 v[36:37], 0
	v_mov_b64_e32 v[38:39], 0
	v_mov_b64_e32 v[40:41], 0
	v_mov_b64_e32 v[42:43], 0
	v_mov_b64_e32 v[44:45], 0
	v_mov_b64_e32 v[46:47], 0
	v_mov_b64_e32 v[48:49], 0
	v_mov_b64_e32 v[50:51], 0
	v_mov_b64_e32 v[52:53], 0
	v_mov_b64_e32 v[54:55], 0
	v_mov_b64_e32 v[56:57], 0
	v_mov_b64_e32 v[58:59], 0
	v_mov_b64_e32 v[60:61], 0
	v_mov_b64_e32 v[62:63], 0
	v_mov_b64_e32 v[64:65], 0
	v_mov_b64_e32 v[66:67], 0
	v_mov_b64_e32 v[68:69], 0
	v_mov_b64_e32 v[70:71], 0
	v_mov_b64_e32 v[72:73], 0
	v_mov_b64_e32 v[74:75], 0
	v_mov_b64_e32 v[76:77], 0
	v_mov_b64_e32 v[78:79], 0
	v_mov_b64_e32 v[80:81], 0
	v_mov_b64_e32 v[82:83], 0
	v_mov_b64_e32 v[84:85], 0
	v_mov_b64_e32 v[86:87], 0
	v_mov_b64_e32 v[88:89], 0
	v_mov_b64_e32 v[90:91], 0
	v_mov_b64_e32 v[92:93], 0
	v_mov_b64_e32 v[94:95], 0
	v_mov_b64_e32 v[96:97], 0
	v_mov_b64_e32 v[98:99], 0
	v_mov_b64_e32 v[100:101], 0
	v_mov_b64_e32 v[102:103], 0
	v_mov_b64_e32 v[104:105], 0
	v_mov_b64_e32 v[106:107], 0
	v_mov_b64_e32 v[108:109], 0
	v_mov_b64_e32 v[110:111], 0
	v_mov_b64_e32 v[112:113], 0
	v_mov_b64_e32 v[114:115], 0
	v_mov_b64_e32 v[116:117], 0
	v_mov_b64_e32 v[118:119], 0
	v_mov_b64_e32 v[120:121], 0
	v_mov_b64_e32 v[122:123], 0
	v_mov_b64_e32 v[124:125], 0
	v_mov_b64_e32 v[126:127], 0
	s_barrier
.LBB0_943:
	s_add_u32 s12, s10, 0xf3ce0080
	s_addc_u32 s13, s11, -1
	s_cmp_lg_u32 s20, 4
	s_cselect_b32 s12, s12, 0
	s_cselect_b32 s13, s13, 0
	s_add_u32 s14, s6, s12
	s_addc_u32 s15, s7, s13
	s_add_i32 s21, 0, 0x10000
	v_add_u32_e32 v150, s21, v140
	ds_read_b128 v[142:145], v150
	ds_read_b128 v[146:149], v150 offset:1024
	ds_read_b128 v[154:157], v150 offset:2048
	ds_read_b128 v[158:161], v150 offset:3072
	s_add_u32 s12, s8, s12
	s_addc_u32 s13, s9, s13
	v_lshl_add_u64 v[150:151], v[136:137], 0, s[10:11]
	s_add_i32 m0, s22, 0xc000
	ds_read_b128 v[162:165], v141
	ds_read_b128 v[166:169], v141 offset:1024
	ds_read_b128 v[170:173], v141 offset:2048
	ds_read_b128 v[174:177], v141 offset:3072
	ds_read_b128 v[180:183], v141 offset:4096
	ds_read_b128 v[184:187], v141 offset:5120
	ds_read_b128 v[188:191], v141 offset:6144
	ds_read_b128 v[192:195], v141 offset:7168
	global_load_lds_dwordx4 v[150:151], off
	v_lshl_add_u64 v[150:151], v[134:135], 0, s[10:11]
	s_add_i32 m0, s22, 0xe000
	s_nop 0
	global_load_lds_dwordx4 v[150:151], off
	s_waitcnt lgkmcnt(8)
	s_barrier
	s_waitcnt lgkmcnt(0)
	v_mfma_f32_16x16x32_bf16 v[124:127], v[142:145], v[162:165], v[124:127]
	v_mfma_f32_16x16x32_bf16 v[120:123], v[154:157], v[162:165], v[120:123]
	v_mfma_f32_16x16x32_bf16 v[116:119], v[142:145], v[170:173], v[116:119]
	v_mfma_f32_16x16x32_bf16 v[108:111], v[154:157], v[170:173], v[108:111]
	v_mfma_f32_16x16x32_bf16 v[100:103], v[142:145], v[180:183], v[100:103]
	v_mfma_f32_16x16x32_bf16 v[92:95], v[154:157], v[180:183], v[92:95]
	v_mfma_f32_16x16x32_bf16 v[84:87], v[142:145], v[188:191], v[84:87]
	v_mfma_f32_16x16x32_bf16 v[76:79], v[154:157], v[188:191], v[76:79]
	v_mfma_f32_16x16x32_bf16 v[124:127], v[146:149], v[166:169], v[124:127]
	v_mfma_f32_16x16x32_bf16 v[120:123], v[158:161], v[166:169], v[120:123]
	v_mfma_f32_16x16x32_bf16 v[116:119], v[146:149], v[174:177], v[116:119]
	v_mfma_f32_16x16x32_bf16 v[108:111], v[158:161], v[174:177], v[108:111]
	v_mfma_f32_16x16x32_bf16 v[100:103], v[146:149], v[184:187], v[100:103]
	v_mfma_f32_16x16x32_bf16 v[92:95], v[158:161], v[184:187], v[92:95]
	v_mfma_f32_16x16x32_bf16 v[84:87], v[146:149], v[192:195], v[84:87]
	v_mfma_f32_16x16x32_bf16 v[76:79], v[158:161], v[192:195], v[76:79]
	s_barrier
	s_add_i32 s28, 0, 0x14000
	v_add_u32_e32 v150, s28, v140
	s_add_i32 s21, s21, s16
	ds_read_b128 v[196:199], v150
	ds_read_b128 v[224:227], v150 offset:1024
	ds_read_b128 v[228:231], v150 offset:2048
	ds_read_b128 v[232:235], v150 offset:3072
	s_mov_b32 m0, s21
	s_nop 0
	global_load_lds_dwordx4 v178, s[12:13]
	s_add_i32 m0, s21, 0x2000
	s_nop 0
	global_load_lds_dwordx4 v128, s[12:13]
	s_barrier
	s_waitcnt lgkmcnt(0)
	v_mfma_f32_16x16x32_bf16 v[112:115], v[196:199], v[162:165], v[112:115]
	v_mfma_f32_16x16x32_bf16 v[104:107], v[228:231], v[162:165], v[104:107]
	v_mfma_f32_16x16x32_bf16 v[96:99], v[196:199], v[170:173], v[96:99]
	v_mfma_f32_16x16x32_bf16 v[88:91], v[228:231], v[170:173], v[88:91]
	v_mfma_f32_16x16x32_bf16 v[80:83], v[196:199], v[180:183], v[80:83]
	v_mfma_f32_16x16x32_bf16 v[72:75], v[228:231], v[180:183], v[72:75]
	v_mfma_f32_16x16x32_bf16 v[68:71], v[196:199], v[188:191], v[68:71]
	v_mfma_f32_16x16x32_bf16 v[64:67], v[228:231], v[188:191], v[64:67]
	v_mfma_f32_16x16x32_bf16 v[112:115], v[224:227], v[166:169], v[112:115]
	v_mfma_f32_16x16x32_bf16 v[104:107], v[232:235], v[166:169], v[104:107]
	v_mfma_f32_16x16x32_bf16 v[96:99], v[224:227], v[174:177], v[96:99]
	v_mfma_f32_16x16x32_bf16 v[88:91], v[232:235], v[174:177], v[88:91]
	v_mfma_f32_16x16x32_bf16 v[80:83], v[224:227], v[184:187], v[80:83]
	v_mfma_f32_16x16x32_bf16 v[72:75], v[232:235], v[184:187], v[72:75]
	v_mfma_f32_16x16x32_bf16 v[68:71], v[224:227], v[192:195], v[68:71]
	v_mfma_f32_16x16x32_bf16 v[64:67], v[232:235], v[192:195], v[64:67]
	s_mov_b32 m0, s22
	s_mov_b64 s[100:101], s[14:15]
	s_barrier
	ds_read_b128 v[162:165], v141 offset:16384
	ds_read_b128 v[166:169], v141 offset:17408
	ds_read_b128 v[170:173], v141 offset:18432
	ds_read_b128 v[174:177], v141 offset:19456
	ds_read_b128 v[180:183], v141 offset:20480
	ds_read_b128 v[184:187], v141 offset:21504
	ds_read_b128 v[188:191], v141 offset:22528
	ds_read_b128 v[192:195], v141 offset:23552
	global_load_lds_dwordx4 v132, s[14:15]
	s_mov_b64 s[100:101], s[14:15]
	s_mov_b32 m0, s23
	s_nop 0
	global_load_lds_dwordx4 v130, s[14:15]
	s_barrier
	s_waitcnt lgkmcnt(0)
	v_mfma_f32_16x16x32_bf16 v[60:63], v[142:145], v[162:165], v[60:63]
	v_mfma_f32_16x16x32_bf16 v[56:59], v[154:157], v[162:165], v[56:59]
	v_mfma_f32_16x16x32_bf16 v[52:55], v[142:145], v[170:173], v[52:55]
	v_mfma_f32_16x16x32_bf16 v[44:47], v[154:157], v[170:173], v[44:47]
	v_mfma_f32_16x16x32_bf16 v[36:39], v[142:145], v[180:183], v[36:39]
	v_mfma_f32_16x16x32_bf16 v[28:31], v[154:157], v[180:183], v[28:31]
	v_mfma_f32_16x16x32_bf16 v[20:23], v[142:145], v[188:191], v[20:23]
	v_mfma_f32_16x16x32_bf16 v[12:15], v[154:157], v[188:191], v[12:15]
	v_mfma_f32_16x16x32_bf16 v[60:63], v[146:149], v[166:169], v[60:63]
	v_mfma_f32_16x16x32_bf16 v[56:59], v[158:161], v[166:169], v[56:59]
	v_mfma_f32_16x16x32_bf16 v[52:55], v[146:149], v[174:177], v[52:55]
	v_mfma_f32_16x16x32_bf16 v[44:47], v[158:161], v[174:177], v[44:47]
	v_mfma_f32_16x16x32_bf16 v[36:39], v[146:149], v[184:187], v[36:39]
	v_mfma_f32_16x16x32_bf16 v[28:31], v[158:161], v[184:187], v[28:31]
	v_mfma_f32_16x16x32_bf16 v[20:23], v[146:149], v[192:195], v[20:23]
	v_mfma_f32_16x16x32_bf16 v[12:15], v[158:161], v[192:195], v[12:15]
	s_barrier
	s_add_u32 s26, s12, 0x20000
	s_addc_u32 s27, s13, 0
	s_add_i32 s21, s28, s16
	s_mov_b32 m0, s21
	s_nop 0
	global_load_lds_dwordx4 v178, s[26:27]
	s_add_i32 m0, s21, 0x2000
	s_nop 0
	global_load_lds_dwordx4 v128, s[26:27]
	s_waitcnt vmcnt(6)
	s_barrier
	v_mfma_f32_16x16x32_bf16 v[48:51], v[196:199], v[162:165], v[48:51]
	v_mfma_f32_16x16x32_bf16 v[40:43], v[228:231], v[162:165], v[40:43]
	v_mfma_f32_16x16x32_bf16 v[32:35], v[196:199], v[170:173], v[32:35]
	v_mfma_f32_16x16x32_bf16 v[24:27], v[228:231], v[170:173], v[24:27]
	v_mfma_f32_16x16x32_bf16 v[16:19], v[196:199], v[180:183], v[16:19]
	v_mfma_f32_16x16x32_bf16 v[8:11], v[228:231], v[180:183], v[8:11]
	v_mfma_f32_16x16x32_bf16 v[4:7], v[196:199], v[188:191], v[4:7]
	v_mfma_f32_16x16x32_bf16 v[0:3], v[228:231], v[188:191], v[0:3]
	v_mfma_f32_16x16x32_bf16 v[48:51], v[224:227], v[166:169], v[48:51]
	v_mfma_f32_16x16x32_bf16 v[40:43], v[232:235], v[166:169], v[40:43]
	v_mfma_f32_16x16x32_bf16 v[32:35], v[224:227], v[174:177], v[32:35]
	v_mfma_f32_16x16x32_bf16 v[24:27], v[232:235], v[174:177], v[24:27]
	v_mfma_f32_16x16x32_bf16 v[16:19], v[224:227], v[184:187], v[16:19]
	v_mfma_f32_16x16x32_bf16 v[8:11], v[232:235], v[184:187], v[8:11]
	v_mfma_f32_16x16x32_bf16 v[4:7], v[224:227], v[192:195], v[4:7]
	v_mfma_f32_16x16x32_bf16 v[0:3], v[232:235], v[192:195], v[0:3]
	s_add_i32 s21, 0, 0x18000
	v_add_u32_e32 v153, s21, v140
	s_barrier
	ds_read_b128 v[142:145], v153
	ds_read_b128 v[146:149], v153 offset:1024
	ds_read_b128 v[154:157], v153 offset:2048
	ds_read_b128 v[158:161], v153 offset:3072
	s_add_u32 s14, s14, 0x20000
	s_addc_u32 s15, s15, 0
	s_mov_b32 m0, s24
	ds_read_b128 v[162:165], v141 offset:32768
	ds_read_b128 v[166:169], v141 offset:33792
	ds_read_b128 v[170:173], v141 offset:34816
	ds_read_b128 v[174:177], v141 offset:35840
	ds_read_b128 v[180:183], v141 offset:36864
	ds_read_b128 v[184:187], v141 offset:37888
	ds_read_b128 v[188:191], v141 offset:38912
	ds_read_b128 v[192:195], v141 offset:39936
	global_load_lds_dwordx4 v132, s[14:15]
	s_mov_b32 m0, s25
	s_nop 0
	global_load_lds_dwordx4 v130, s[14:15]
	s_waitcnt lgkmcnt(8)
	s_barrier
	s_waitcnt lgkmcnt(0)
	v_mfma_f32_16x16x32_bf16 v[124:127], v[142:145], v[162:165], v[124:127]
	v_mfma_f32_16x16x32_bf16 v[120:123], v[154:157], v[162:165], v[120:123]
	v_mfma_f32_16x16x32_bf16 v[116:119], v[142:145], v[170:173], v[116:119]
	v_mfma_f32_16x16x32_bf16 v[108:111], v[154:157], v[170:173], v[108:111]
	v_mfma_f32_16x16x32_bf16 v[100:103], v[142:145], v[180:183], v[100:103]
	v_mfma_f32_16x16x32_bf16 v[92:95], v[154:157], v[180:183], v[92:95]
	v_mfma_f32_16x16x32_bf16 v[84:87], v[142:145], v[188:191], v[84:87]
	v_mfma_f32_16x16x32_bf16 v[76:79], v[154:157], v[188:191], v[76:79]
	v_mfma_f32_16x16x32_bf16 v[124:127], v[146:149], v[166:169], v[124:127]
	v_mfma_f32_16x16x32_bf16 v[120:123], v[158:161], v[166:169], v[120:123]
	v_mfma_f32_16x16x32_bf16 v[116:119], v[146:149], v[174:177], v[116:119]
	v_mfma_f32_16x16x32_bf16 v[108:111], v[158:161], v[174:177], v[108:111]
	v_mfma_f32_16x16x32_bf16 v[100:103], v[146:149], v[184:187], v[100:103]
	v_mfma_f32_16x16x32_bf16 v[92:95], v[158:161], v[184:187], v[92:95]
	v_mfma_f32_16x16x32_bf16 v[84:87], v[146:149], v[192:195], v[84:87]
	v_mfma_f32_16x16x32_bf16 v[76:79], v[158:161], v[192:195], v[76:79]
	s_barrier
	s_add_i32 s14, 0, 0x1c000
	s_add_i32 s15, s21, s16
	v_add_u32_e32 v153, s14, v140
	s_add_i32 m0, s15, 0xffffff80
	ds_read_b128 v[196:199], v153
	ds_read_b128 v[224:227], v153 offset:1024
	ds_read_b128 v[228:231], v153 offset:2048
	ds_read_b128 v[232:235], v153 offset:3072
	global_load_lds_dwordx4 v178, s[12:13] offset:128
	s_add_i32 m0, s15, 0x1f80
	s_nop 0
	global_load_lds_dwordx4 v128, s[12:13] offset:128
	s_barrier
	s_waitcnt lgkmcnt(0)
	v_mfma_f32_16x16x32_bf16 v[112:115], v[196:199], v[162:165], v[112:115]
	v_mfma_f32_16x16x32_bf16 v[104:107], v[228:231], v[162:165], v[104:107]
	v_mfma_f32_16x16x32_bf16 v[96:99], v[196:199], v[170:173], v[96:99]
	v_mfma_f32_16x16x32_bf16 v[88:91], v[228:231], v[170:173], v[88:91]
	v_mfma_f32_16x16x32_bf16 v[80:83], v[196:199], v[180:183], v[80:83]
	v_mfma_f32_16x16x32_bf16 v[72:75], v[228:231], v[180:183], v[72:75]
	v_mfma_f32_16x16x32_bf16 v[68:71], v[196:199], v[188:191], v[68:71]
	v_mfma_f32_16x16x32_bf16 v[64:67], v[228:231], v[188:191], v[64:67]
	v_mfma_f32_16x16x32_bf16 v[112:115], v[224:227], v[166:169], v[112:115]
	v_mfma_f32_16x16x32_bf16 v[104:107], v[232:235], v[166:169], v[104:107]
	v_mfma_f32_16x16x32_bf16 v[96:99], v[224:227], v[174:177], v[96:99]
	v_mfma_f32_16x16x32_bf16 v[88:91], v[232:235], v[174:177], v[88:91]
	v_mfma_f32_16x16x32_bf16 v[80:83], v[224:227], v[184:187], v[80:83]
	v_mfma_f32_16x16x32_bf16 v[72:75], v[232:235], v[184:187], v[72:75]
	v_mfma_f32_16x16x32_bf16 v[68:71], v[224:227], v[192:195], v[68:71]
	v_mfma_f32_16x16x32_bf16 v[64:67], v[232:235], v[192:195], v[64:67]
	s_add_i32 m0, s18, 0xffffff80
	s_barrier
	ds_read_b128 v[162:165], v141 offset:49152
	ds_read_b128 v[166:169], v141 offset:50176
	ds_read_b128 v[170:173], v141 offset:51200
	ds_read_b128 v[174:177], v141 offset:52224
	ds_read_b128 v[180:183], v141 offset:53248
	ds_read_b128 v[184:187], v141 offset:54272
	ds_read_b128 v[188:191], v141 offset:55296
	ds_read_b128 v[192:195], v141 offset:56320
	global_load_lds_dwordx4 v132, s[100:101] offset:128
	s_add_i32 m0, s19, 0xffffff80
	s_nop 0
	global_load_lds_dwordx4 v130, s[100:101] offset:128
	s_barrier
	s_waitcnt lgkmcnt(0)
	v_mfma_f32_16x16x32_bf16 v[60:63], v[142:145], v[162:165], v[60:63]
	v_mfma_f32_16x16x32_bf16 v[56:59], v[154:157], v[162:165], v[56:59]
	v_mfma_f32_16x16x32_bf16 v[52:55], v[142:145], v[170:173], v[52:55]
	v_mfma_f32_16x16x32_bf16 v[44:47], v[154:157], v[170:173], v[44:47]
	v_mfma_f32_16x16x32_bf16 v[36:39], v[142:145], v[180:183], v[36:39]
	v_mfma_f32_16x16x32_bf16 v[28:31], v[154:157], v[180:183], v[28:31]
	v_mfma_f32_16x16x32_bf16 v[20:23], v[142:145], v[188:191], v[20:23]
	v_mfma_f32_16x16x32_bf16 v[12:15], v[154:157], v[188:191], v[12:15]
	v_mfma_f32_16x16x32_bf16 v[60:63], v[146:149], v[166:169], v[60:63]
	v_mfma_f32_16x16x32_bf16 v[56:59], v[158:161], v[166:169], v[56:59]
	v_mfma_f32_16x16x32_bf16 v[52:55], v[146:149], v[174:177], v[52:55]
	v_mfma_f32_16x16x32_bf16 v[44:47], v[158:161], v[174:177], v[44:47]
	v_mfma_f32_16x16x32_bf16 v[36:39], v[146:149], v[184:187], v[36:39]
	v_mfma_f32_16x16x32_bf16 v[28:31], v[158:161], v[184:187], v[28:31]
	v_mfma_f32_16x16x32_bf16 v[20:23], v[146:149], v[192:195], v[20:23]
	v_mfma_f32_16x16x32_bf16 v[12:15], v[158:161], v[192:195], v[12:15]
	s_barrier
	s_add_u32 s12, s12, 0x20080
	s_addc_u32 s13, s13, 0
	s_add_i32 s14, s14, s16
	s_mov_b32 m0, s14
	s_nop 0
	global_load_lds_dwordx4 v178, s[12:13]
	s_add_i32 m0, s14, 0x2000
	s_nop 0
	global_load_lds_dwordx4 v128, s[12:13]
	s_waitcnt vmcnt(6)
	s_barrier
	v_mfma_f32_16x16x32_bf16 v[48:51], v[196:199], v[162:165], v[48:51]
	v_mfma_f32_16x16x32_bf16 v[40:43], v[228:231], v[162:165], v[40:43]
	v_mfma_f32_16x16x32_bf16 v[32:35], v[196:199], v[170:173], v[32:35]
	v_mfma_f32_16x16x32_bf16 v[24:27], v[228:231], v[170:173], v[24:27]
	v_mfma_f32_16x16x32_bf16 v[16:19], v[196:199], v[180:183], v[16:19]
	v_mfma_f32_16x16x32_bf16 v[8:11], v[228:231], v[180:183], v[8:11]
	v_mfma_f32_16x16x32_bf16 v[4:7], v[196:199], v[188:191], v[4:7]
	v_mfma_f32_16x16x32_bf16 v[0:3], v[228:231], v[188:191], v[0:3]
	v_mfma_f32_16x16x32_bf16 v[48:51], v[224:227], v[166:169], v[48:51]
	v_mfma_f32_16x16x32_bf16 v[40:43], v[232:235], v[166:169], v[40:43]
	v_mfma_f32_16x16x32_bf16 v[32:35], v[224:227], v[174:177], v[32:35]
	v_mfma_f32_16x16x32_bf16 v[24:27], v[232:235], v[174:177], v[24:27]
	v_mfma_f32_16x16x32_bf16 v[16:19], v[224:227], v[184:187], v[16:19]
	v_mfma_f32_16x16x32_bf16 v[8:11], v[232:235], v[184:187], v[8:11]
	v_mfma_f32_16x16x32_bf16 v[4:7], v[224:227], v[192:195], v[4:7]
	v_mfma_f32_16x16x32_bf16 v[0:3], v[232:235], v[192:195], v[0:3]
	s_add_i32 s20, s20, 2
	s_add_u32 s10, s10, 0x100
	s_addc_u32 s11, s11, 0
	s_cmp_gt_u32 s20, 5
	s_barrier
	s_cbranch_scc0 .LBB0_943
	v_readlane_b32 s6, v254, 23
	s_or_b32 s6, s17, s6
	v_cvt_pk_bf16_f32 v124, v124, v125
	v_cvt_pk_bf16_f32 v125, v126, v127
	v_cvt_pk_bf16_f32 v126, v120, v121
	v_cvt_pk_bf16_f32 v127, v122, v123
	s_nop 0
	v_or_b32_e32 v132, s6, v139
	v_readlane_b32 s6, v254, 25
	v_lshlrev_b32_e32 v178, 1, v132
	s_nop 0
	v_add_u32_e32 v128, s6, v138
	v_ashrrev_i32_e32 v129, 31, v128
	v_lshlrev_b64 v[130:131], 12, v[128:129]
	v_lshl_add_u64 v[130:131], s[4:5], 0, v[130:131]
	v_lshl_add_u64 v[130:131], v[130:131], 0, v[178:179]
	global_store_dwordx4 v[130:131], v[124:127], off
	v_cvt_pk_bf16_f32 v112, v112, v113
	v_cvt_pk_bf16_f32 v113, v114, v115
	v_cvt_pk_bf16_f32 v114, v104, v105
	v_or_b32_e32 v104, 16, v128
	v_ashrrev_i32_e32 v105, 31, v104
	v_lshlrev_b64 v[104:105], 12, v[104:105]
	v_lshl_add_u64 v[104:105], s[4:5], 0, v[104:105]
	v_cvt_pk_bf16_f32 v115, v106, v107
	global_store_dwordx4 v[130:131], v[112:115], off offset:256
	s_nop 1
	v_lshl_add_u64 v[112:113], v[104:105], 0, v[178:179]
	v_cvt_pk_bf16_f32 v104, v116, v117
	v_cvt_pk_bf16_f32 v105, v118, v119
	v_cvt_pk_bf16_f32 v106, v108, v109
	v_cvt_pk_bf16_f32 v107, v110, v111
	global_store_dwordx4 v[112:113], v[104:107], off
	v_cvt_pk_bf16_f32 v96, v96, v97
	v_cvt_pk_bf16_f32 v97, v98, v99
	v_cvt_pk_bf16_f32 v98, v88, v89
	v_or_b32_e32 v88, 32, v128
	v_ashrrev_i32_e32 v89, 31, v88
	v_lshlrev_b64 v[88:89], 12, v[88:89]
	v_lshl_add_u64 v[88:89], s[4:5], 0, v[88:89]
	v_cvt_pk_bf16_f32 v99, v90, v91
	global_store_dwordx4 v[112:113], v[96:99], off offset:256
	s_nop 1
	v_lshl_add_u64 v[96:97], v[88:89], 0, v[178:179]
	v_cvt_pk_bf16_f32 v88, v100, v101
	v_cvt_pk_bf16_f32 v89, v102, v103
	v_cvt_pk_bf16_f32 v90, v92, v93
	v_cvt_pk_bf16_f32 v91, v94, v95
	global_store_dwordx4 v[96:97], v[88:91], off
	v_cvt_pk_bf16_f32 v80, v80, v81
	v_cvt_pk_bf16_f32 v81, v82, v83
	v_cvt_pk_bf16_f32 v82, v72, v73
	v_or_b32_e32 v72, 48, v128
	v_ashrrev_i32_e32 v73, 31, v72
	v_lshlrev_b64 v[72:73], 12, v[72:73]
	v_lshl_add_u64 v[72:73], s[4:5], 0, v[72:73]
	v_cvt_pk_bf16_f32 v83, v74, v75
	global_store_dwordx4 v[96:97], v[80:83], off offset:256
	s_nop 1
	v_lshl_add_u64 v[80:81], v[72:73], 0, v[178:179]
	v_cvt_pk_bf16_f32 v72, v84, v85
	v_cvt_pk_bf16_f32 v73, v86, v87
	v_cvt_pk_bf16_f32 v74, v76, v77
	v_cvt_pk_bf16_f32 v75, v78, v79
	global_store_dwordx4 v[80:81], v[72:75], off
	v_cvt_pk_bf16_f32 v68, v68, v69
	v_cvt_pk_bf16_f32 v69, v70, v71
	v_cvt_pk_bf16_f32 v70, v64, v65
	v_add_u32_e32 v64, 0x80, v128
	v_ashrrev_i32_e32 v65, 31, v64
	v_lshlrev_b64 v[64:65], 12, v[64:65]
	v_lshl_add_u64 v[64:65], s[4:5], 0, v[64:65]
	v_lshl_add_u64 v[64:65], v[64:65], 0, v[178:179]
	v_cvt_pk_bf16_f32 v71, v66, v67
	global_store_dwordx4 v[80:81], v[68:71], off offset:256
	v_cvt_pk_bf16_f32 v60, v60, v61
	v_cvt_pk_bf16_f32 v61, v62, v63
	v_cvt_pk_bf16_f32 v62, v56, v57
	v_cvt_pk_bf16_f32 v63, v58, v59
	global_store_dwordx4 v[64:65], v[60:63], off
	v_cvt_pk_bf16_f32 v48, v48, v49
	v_cvt_pk_bf16_f32 v49, v50, v51
	v_cvt_pk_bf16_f32 v50, v40, v41
	v_add_u32_e32 v40, 0x90, v128
	v_ashrrev_i32_e32 v41, 31, v40
	v_lshlrev_b64 v[40:41], 12, v[40:41]
	v_lshl_add_u64 v[40:41], s[4:5], 0, v[40:41]
	v_cvt_pk_bf16_f32 v51, v42, v43
	global_store_dwordx4 v[64:65], v[48:51], off offset:256
	s_nop 1
	v_lshl_add_u64 v[48:49], v[40:41], 0, v[178:179]
	v_cvt_pk_bf16_f32 v40, v52, v53
	v_cvt_pk_bf16_f32 v41, v54, v55
	v_cvt_pk_bf16_f32 v42, v44, v45
	v_cvt_pk_bf16_f32 v43, v46, v47
	global_store_dwordx4 v[48:49], v[40:43], off
	v_cvt_pk_bf16_f32 v32, v32, v33
	v_cvt_pk_bf16_f32 v33, v34, v35
	v_cvt_pk_bf16_f32 v34, v24, v25
	v_add_u32_e32 v24, 0xa0, v128
	v_ashrrev_i32_e32 v25, 31, v24
	v_lshlrev_b64 v[24:25], 12, v[24:25]
	v_lshl_add_u64 v[24:25], s[4:5], 0, v[24:25]
	v_cvt_pk_bf16_f32 v35, v26, v27
	global_store_dwordx4 v[48:49], v[32:35], off offset:256
	s_nop 1
	v_lshl_add_u64 v[32:33], v[24:25], 0, v[178:179]
	v_cvt_pk_bf16_f32 v24, v36, v37
	v_cvt_pk_bf16_f32 v25, v38, v39
	v_cvt_pk_bf16_f32 v26, v28, v29
	v_cvt_pk_bf16_f32 v27, v30, v31
	global_store_dwordx4 v[32:33], v[24:27], off
	v_cvt_pk_bf16_f32 v16, v16, v17
	v_cvt_pk_bf16_f32 v17, v18, v19
	v_cvt_pk_bf16_f32 v18, v8, v9
	v_add_u32_e32 v8, 0xb0, v128
	v_ashrrev_i32_e32 v9, 31, v8
	v_lshlrev_b64 v[8:9], 12, v[8:9]
	v_lshl_add_u64 v[8:9], s[4:5], 0, v[8:9]
	v_cvt_pk_bf16_f32 v19, v10, v11
	global_store_dwordx4 v[32:33], v[16:19], off offset:256
	v_readlane_b32 s4, v255, 8
	s_nop 0
	v_lshl_add_u64 v[16:17], v[8:9], 0, v[178:179]
	v_cvt_pk_bf16_f32 v8, v20, v21
	v_cvt_pk_bf16_f32 v9, v22, v23
	v_cvt_pk_bf16_f32 v10, v12, v13
	v_cvt_pk_bf16_f32 v11, v14, v15
	global_store_dwordx4 v[16:17], v[8:11], off
	v_cvt_pk_bf16_f32 v4, v4, v5
	v_cvt_pk_bf16_f32 v5, v6, v7
	v_cvt_pk_bf16_f32 v6, v0, v1
	v_cvt_pk_bf16_f32 v7, v2, v3
	global_store_dwordx4 v[16:17], v[4:7], off offset:256
	s_waitcnt vmcnt(0)
	s_cmp_lt_u32 s4, 4
	s_cbranch_scc0 .LBB0_946
	s_barrier

.LBB0_1073:
	v_readlane_b32 s6, v255, 20
	v_readlane_b32 s7, v255, 21
	s_lshl_b64 s[6:7], s[6:7], 2
	s_add_u32 s5, s88, s6
	s_addc_u32 s6, s89, s7
	v_bfe_u32 v18, v16, 4, 2
	s_add_u32 s35, s5, 0xc344000
	v_and_b32_e32 v17, 15, v16
	v_lshlrev_b32_e32 v19, 4, v18
	v_lshlrev_b32_e32 v16, 2, v16
	s_addc_u32 s39, s6, 0
	v_lshl_or_b32 v156, s4, 6, v17
	v_lshl_or_b32 v17, v17, 6, v19
	s_lshl_b32 s4, s4, 13
	v_and_b32_e32 v16, 32, v16
	v_bitop3_b32 v19, v17, s4, v16 bitop3:0xde
	s_lshl_b32 s4, s86, 5
	s_and_b32 s6, s4, 0x60
	s_add_i32 m0, s29, 0x18000
	v_lshl_add_u64 v[6:7], v[6:7], 0, s[54:55]
	s_lshl_b32 s4, s6, 7
	s_waitcnt vmcnt(4)
	s_barrier
	global_load_lds_dwordx4 v[6:7], off
	v_lshl_add_u64 v[4:5], v[4:5], 0, s[54:55]
	s_add_i32 m0, s29, 0x1a000
	s_add_i32 s56, s29, 0x8000
	s_add_i32 s57, s29, 0xa000
	v_bitop3_b32 v157, v17, s4, v16 bitop3:0xde
	global_load_lds_dwordx4 v[4:5], off
	v_lshl_add_u64 v[2:3], v[2:3], 0, s[54:55]
	s_mov_b32 m0, s56
	s_add_u32 s4, s18, 0x80080
	global_load_lds_dwordx4 v[2:3], off
	v_lshl_add_u64 v[0:1], v[0:1], 0, s[54:55]
	s_mov_b32 m0, s57
	s_addc_u32 s5, s19, 0
	global_load_lds_dwordx4 v[0:1], off
	s_add_i32 m0, s29, 0x1c000
	s_nop 0
	global_load_lds_dwordx4 v178, s[4:5]
	v_lshl_add_u64 v[0:1], s[4:5], 0, v[144:145]
	s_add_i32 m0, s29, 0x1e000
	s_mov_b64 s[4:5], 0x80080
	global_load_lds_dwordx4 v[0:1], off
	v_lshlrev_b32_e32 v0, 14, v8
	v_and_b32_e32 v0, 0x7fff8000, v0
	v_lshl_add_u32 v0, v9, 11, v0
	v_or_b32_e32 v0, v0, v10
	v_add_lshl_u32 v0, v0, v11, 1
	v_mov_b32_e32 v1, v179
	v_lshl_add_u64 v[146:147], v[0:1], 0, s[4:5]
	v_lshlrev_b32_e32 v0, 14, v12
	v_and_b32_e32 v0, 0x7fff8000, v0
	v_lshl_add_u32 v0, v13, 11, v0
	s_waitcnt vmcnt(6)
	v_or_b32_e32 v0, v0, v14
	v_add_lshl_u32 v0, v0, v15, 1
	v_lshl_or_b32 v158, v18, 2, s6
	v_lshl_add_u64 v[148:149], v[0:1], 0, s[4:5]
	s_mov_b32 s58, 0
	v_add_u32_e32 v159, 0, v19
	s_barrier

.LBB0_1077:
	s_add_u32 s18, s16, 0x100
	s_addc_u32 s19, s17, 0
	s_add_i32 s66, 0, 0x10000
	v_add_u32_e32 v140, s66, v157
	ds_read_b128 v[128:131], v140
	ds_read_b128 v[132:135], v140 offset:1024
	ds_read_b128 v[136:139], v140 offset:2048
	ds_read_b128 v[140:143], v140 offset:3072
	s_cmp_eq_u32 s63, 28
	s_cselect_b32 s23, s13, s19
	s_cselect_b32 s22, s12, s18
	s_cselect_b32 s21, s15, s62
	s_cselect_b32 s20, s14, s5
	v_lshl_add_u64 v[154:155], s[16:17], 0, v[148:149]
	s_add_i32 m0, s29, 0xc000
	ds_read_b128 v[150:153], v159
	ds_read_b128 v[160:163], v159 offset:1024
	ds_read_b128 v[164:167], v159 offset:2048
	ds_read_b128 v[168:171], v159 offset:3072
	ds_read_b128 v[172:175], v159 offset:4096
	ds_read_b128 v[180:183], v159 offset:5120
	ds_read_b128 v[184:187], v159 offset:6144
	ds_read_b128 v[188:191], v159 offset:7168
	global_load_lds_dwordx4 v[154:155], off
	v_lshl_add_u64 v[154:155], s[16:17], 0, v[146:147]
	s_add_i32 m0, s29, 0xe000
	s_nop 0
	global_load_lds_dwordx4 v[154:155], off
	s_waitcnt lgkmcnt(8)
	s_barrier
	s_waitcnt lgkmcnt(0)
	v_mfma_f32_16x16x32_bf16 v[124:127], v[128:131], v[150:153], v[124:127]
	v_mfma_f32_16x16x32_bf16 v[120:123], v[136:139], v[150:153], v[120:123]
	v_mfma_f32_16x16x32_bf16 v[108:111], v[128:131], v[164:167], v[108:111]
	v_mfma_f32_16x16x32_bf16 v[104:107], v[136:139], v[164:167], v[104:107]
	v_mfma_f32_16x16x32_bf16 v[92:95], v[128:131], v[172:175], v[92:95]
	v_mfma_f32_16x16x32_bf16 v[88:91], v[136:139], v[172:175], v[88:91]
	v_mfma_f32_16x16x32_bf16 v[76:79], v[128:131], v[184:187], v[76:79]
	v_mfma_f32_16x16x32_bf16 v[72:75], v[136:139], v[184:187], v[72:75]
	v_mfma_f32_16x16x32_bf16 v[124:127], v[132:135], v[160:163], v[124:127]
	v_mfma_f32_16x16x32_bf16 v[120:123], v[140:143], v[160:163], v[120:123]
	v_mfma_f32_16x16x32_bf16 v[108:111], v[132:135], v[168:171], v[108:111]
	v_mfma_f32_16x16x32_bf16 v[104:107], v[140:143], v[168:171], v[104:107]
	v_mfma_f32_16x16x32_bf16 v[92:95], v[132:135], v[180:183], v[92:95]
	v_mfma_f32_16x16x32_bf16 v[88:91], v[140:143], v[180:183], v[88:91]
	v_mfma_f32_16x16x32_bf16 v[76:79], v[132:135], v[188:191], v[76:79]
	v_mfma_f32_16x16x32_bf16 v[72:75], v[140:143], v[188:191], v[72:75]
	s_barrier
	s_add_i32 s67, 0, 0x14000
	v_add_u32_e32 v154, s67, v157
	s_add_i32 s16, s66, s28
	ds_read_b128 v[192:195], v154
	ds_read_b128 v[196:199], v154 offset:1024
	ds_read_b128 v[204:207], v154 offset:2048
	ds_read_b128 v[212:215], v154 offset:3072
	s_mov_b32 m0, s16
	s_nop 0
	global_load_lds_dwordx4 v178, s[20:21]
	s_add_i32 m0, s16, 0x2000
	s_nop 0
	global_load_lds_dwordx4 v144, s[20:21]
	s_barrier
	s_waitcnt lgkmcnt(0)
	v_mfma_f32_16x16x32_bf16 v[116:119], v[192:195], v[150:153], v[116:119]
	v_mfma_f32_16x16x32_bf16 v[112:115], v[204:207], v[150:153], v[112:115]
	v_mfma_f32_16x16x32_bf16 v[100:103], v[192:195], v[164:167], v[100:103]
	v_mfma_f32_16x16x32_bf16 v[96:99], v[204:207], v[164:167], v[96:99]
	v_mfma_f32_16x16x32_bf16 v[84:87], v[192:195], v[172:175], v[84:87]
	v_mfma_f32_16x16x32_bf16 v[80:83], v[204:207], v[172:175], v[80:83]
	v_mfma_f32_16x16x32_bf16 v[68:71], v[192:195], v[184:187], v[68:71]
	v_mfma_f32_16x16x32_bf16 v[64:67], v[204:207], v[184:187], v[64:67]
	v_mfma_f32_16x16x32_bf16 v[116:119], v[196:199], v[160:163], v[116:119]
	v_mfma_f32_16x16x32_bf16 v[112:115], v[212:215], v[160:163], v[112:115]
	v_mfma_f32_16x16x32_bf16 v[100:103], v[196:199], v[168:171], v[100:103]
	v_mfma_f32_16x16x32_bf16 v[96:99], v[212:215], v[168:171], v[96:99]
	v_mfma_f32_16x16x32_bf16 v[84:87], v[196:199], v[180:183], v[84:87]
	v_mfma_f32_16x16x32_bf16 v[80:83], v[212:215], v[180:183], v[80:83]
	v_mfma_f32_16x16x32_bf16 v[68:71], v[196:199], v[188:191], v[68:71]
	v_mfma_f32_16x16x32_bf16 v[64:67], v[212:215], v[188:191], v[64:67]
	s_mov_b32 m0, s29
	s_mov_b64 s[100:101], s[22:23]
	s_barrier
	ds_read_b128 v[150:153], v159 offset:16384
	ds_read_b128 v[160:163], v159 offset:17408
	ds_read_b128 v[164:167], v159 offset:18432
	ds_read_b128 v[168:171], v159 offset:19456
	ds_read_b128 v[172:175], v159 offset:20480
	ds_read_b128 v[180:183], v159 offset:21504
	ds_read_b128 v[184:187], v159 offset:22528
	ds_read_b128 v[188:191], v159 offset:23552
	global_load_lds_dwordx4 v178, s[22:23]
	s_mov_b64 s[100:101], s[22:23]
	s_mov_b32 m0, s30
	s_nop 0
	global_load_lds_dwordx4 v144, s[22:23]
	s_barrier
	s_waitcnt lgkmcnt(0)
	v_mfma_f32_16x16x32_bf16 v[60:63], v[128:131], v[150:153], v[60:63]
	v_mfma_f32_16x16x32_bf16 v[56:59], v[136:139], v[150:153], v[56:59]
	v_mfma_f32_16x16x32_bf16 v[44:47], v[128:131], v[164:167], v[44:47]
	v_mfma_f32_16x16x32_bf16 v[40:43], v[136:139], v[164:167], v[40:43]
	v_mfma_f32_16x16x32_bf16 v[28:31], v[128:131], v[172:175], v[28:31]
	v_mfma_f32_16x16x32_bf16 v[24:27], v[136:139], v[172:175], v[24:27]
	v_mfma_f32_16x16x32_bf16 v[12:15], v[128:131], v[184:187], v[12:15]
	v_mfma_f32_16x16x32_bf16 v[8:11], v[136:139], v[184:187], v[8:11]
	v_mfma_f32_16x16x32_bf16 v[60:63], v[132:135], v[160:163], v[60:63]
	v_mfma_f32_16x16x32_bf16 v[56:59], v[140:143], v[160:163], v[56:59]
	v_mfma_f32_16x16x32_bf16 v[44:47], v[132:135], v[168:171], v[44:47]
	v_mfma_f32_16x16x32_bf16 v[40:43], v[140:143], v[168:171], v[40:43]
	v_mfma_f32_16x16x32_bf16 v[28:31], v[132:135], v[180:183], v[28:31]
	v_mfma_f32_16x16x32_bf16 v[24:27], v[140:143], v[180:183], v[24:27]
	v_mfma_f32_16x16x32_bf16 v[12:15], v[132:135], v[188:191], v[12:15]
	v_mfma_f32_16x16x32_bf16 v[8:11], v[140:143], v[188:191], v[8:11]
	s_barrier
	s_add_u32 s16, s20, 0x80000
	s_addc_u32 s17, s21, 0
	s_add_i32 s66, s67, s28
	s_mov_b32 m0, s66
	s_nop 0
	global_load_lds_dwordx4 v178, s[16:17]
	s_add_i32 m0, s66, 0x2000
	s_nop 0
	global_load_lds_dwordx4 v144, s[16:17]
	s_waitcnt vmcnt(6)
	s_barrier
	v_mfma_f32_16x16x32_bf16 v[52:55], v[192:195], v[150:153], v[52:55]
	v_mfma_f32_16x16x32_bf16 v[48:51], v[204:207], v[150:153], v[48:51]
	v_mfma_f32_16x16x32_bf16 v[36:39], v[192:195], v[164:167], v[36:39]
	v_mfma_f32_16x16x32_bf16 v[32:35], v[204:207], v[164:167], v[32:35]
	v_mfma_f32_16x16x32_bf16 v[20:23], v[192:195], v[172:175], v[20:23]
	v_mfma_f32_16x16x32_bf16 v[16:19], v[204:207], v[172:175], v[16:19]
	v_mfma_f32_16x16x32_bf16 v[4:7], v[192:195], v[184:187], v[4:7]
	v_mfma_f32_16x16x32_bf16 v[0:3], v[204:207], v[184:187], v[0:3]
	v_mfma_f32_16x16x32_bf16 v[52:55], v[196:199], v[160:163], v[52:55]
	v_mfma_f32_16x16x32_bf16 v[48:51], v[212:215], v[160:163], v[48:51]
	v_mfma_f32_16x16x32_bf16 v[36:39], v[196:199], v[168:171], v[36:39]
	v_mfma_f32_16x16x32_bf16 v[32:35], v[212:215], v[168:171], v[32:35]
	v_mfma_f32_16x16x32_bf16 v[20:23], v[196:199], v[180:183], v[20:23]
	v_mfma_f32_16x16x32_bf16 v[16:19], v[212:215], v[180:183], v[16:19]
	v_mfma_f32_16x16x32_bf16 v[4:7], v[196:199], v[188:191], v[4:7]
	v_mfma_f32_16x16x32_bf16 v[0:3], v[212:215], v[188:191], v[0:3]
	s_add_i32 s66, 0, 0x18000
	v_add_u32_e32 v140, s66, v157
	s_barrier
	ds_read_b128 v[128:131], v140
	ds_read_b128 v[132:135], v140 offset:1024
	ds_read_b128 v[136:139], v140 offset:2048
	ds_read_b128 v[140:143], v140 offset:3072
	s_add_u32 s16, s22, 0x80000
	s_addc_u32 s17, s23, 0
	s_mov_b32 m0, s31
	ds_read_b128 v[150:153], v159 offset:32768
	ds_read_b128 v[160:163], v159 offset:33792
	ds_read_b128 v[164:167], v159 offset:34816
	ds_read_b128 v[168:171], v159 offset:35840
	ds_read_b128 v[172:175], v159 offset:36864
	ds_read_b128 v[180:183], v159 offset:37888
	ds_read_b128 v[184:187], v159 offset:38912
	ds_read_b128 v[188:191], v159 offset:39936
	global_load_lds_dwordx4 v178, s[16:17]
	s_mov_b32 m0, s34
	s_nop 0
	global_load_lds_dwordx4 v144, s[16:17]
	s_waitcnt lgkmcnt(8)
	s_barrier
	s_waitcnt lgkmcnt(0)
	v_mfma_f32_16x16x32_bf16 v[124:127], v[128:131], v[150:153], v[124:127]
	v_mfma_f32_16x16x32_bf16 v[120:123], v[136:139], v[150:153], v[120:123]
	v_mfma_f32_16x16x32_bf16 v[108:111], v[128:131], v[164:167], v[108:111]
	v_mfma_f32_16x16x32_bf16 v[104:107], v[136:139], v[164:167], v[104:107]
	v_mfma_f32_16x16x32_bf16 v[92:95], v[128:131], v[172:175], v[92:95]
	v_mfma_f32_16x16x32_bf16 v[88:91], v[136:139], v[172:175], v[88:91]
	v_mfma_f32_16x16x32_bf16 v[76:79], v[128:131], v[184:187], v[76:79]
	v_mfma_f32_16x16x32_bf16 v[72:75], v[136:139], v[184:187], v[72:75]
	v_mfma_f32_16x16x32_bf16 v[124:127], v[132:135], v[160:163], v[124:127]
	v_mfma_f32_16x16x32_bf16 v[120:123], v[140:143], v[160:163], v[120:123]
	v_mfma_f32_16x16x32_bf16 v[108:111], v[132:135], v[168:171], v[108:111]
	v_mfma_f32_16x16x32_bf16 v[104:107], v[140:143], v[168:171], v[104:107]
	v_mfma_f32_16x16x32_bf16 v[92:95], v[132:135], v[180:183], v[92:95]
	v_mfma_f32_16x16x32_bf16 v[88:91], v[140:143], v[180:183], v[88:91]
	v_mfma_f32_16x16x32_bf16 v[76:79], v[132:135], v[188:191], v[76:79]
	v_mfma_f32_16x16x32_bf16 v[72:75], v[140:143], v[188:191], v[72:75]
	s_barrier
	s_add_i32 s22, 0, 0x1c000
	s_add_i32 s16, s66, s28
	v_add_u32_e32 v212, s22, v157
	s_add_i32 m0, s16, 0xffffff80
	ds_read_b128 v[192:195], v212
	ds_read_b128 v[196:199], v212 offset:1024
	ds_read_b128 v[204:207], v212 offset:2048
	ds_read_b128 v[212:215], v212 offset:3072
	global_load_lds_dwordx4 v178, s[20:21] offset:128
	s_add_i32 m0, s16, 0x1f80
	s_nop 0
	global_load_lds_dwordx4 v144, s[20:21] offset:128
	s_barrier
	s_waitcnt lgkmcnt(0)
	v_mfma_f32_16x16x32_bf16 v[116:119], v[192:195], v[150:153], v[116:119]
	v_mfma_f32_16x16x32_bf16 v[112:115], v[204:207], v[150:153], v[112:115]
	v_mfma_f32_16x16x32_bf16 v[100:103], v[192:195], v[164:167], v[100:103]
	v_mfma_f32_16x16x32_bf16 v[96:99], v[204:207], v[164:167], v[96:99]
	v_mfma_f32_16x16x32_bf16 v[84:87], v[192:195], v[172:175], v[84:87]
	v_mfma_f32_16x16x32_bf16 v[80:83], v[204:207], v[172:175], v[80:83]
	v_mfma_f32_16x16x32_bf16 v[68:71], v[192:195], v[184:187], v[68:71]
	v_mfma_f32_16x16x32_bf16 v[64:67], v[204:207], v[184:187], v[64:67]
	v_mfma_f32_16x16x32_bf16 v[116:119], v[196:199], v[160:163], v[116:119]
	v_mfma_f32_16x16x32_bf16 v[112:115], v[212:215], v[160:163], v[112:115]
	v_mfma_f32_16x16x32_bf16 v[100:103], v[196:199], v[168:171], v[100:103]
	v_mfma_f32_16x16x32_bf16 v[96:99], v[212:215], v[168:171], v[96:99]
	v_mfma_f32_16x16x32_bf16 v[84:87], v[196:199], v[180:183], v[84:87]
	v_mfma_f32_16x16x32_bf16 v[80:83], v[212:215], v[180:183], v[80:83]
	v_mfma_f32_16x16x32_bf16 v[68:71], v[196:199], v[188:191], v[68:71]
	v_mfma_f32_16x16x32_bf16 v[64:67], v[212:215], v[188:191], v[64:67]
	s_add_i32 m0, s56, 0xffffff80
	s_barrier
	ds_read_b128 v[150:153], v159 offset:49152
	ds_read_b128 v[160:163], v159 offset:50176
	ds_read_b128 v[164:167], v159 offset:51200
	ds_read_b128 v[168:171], v159 offset:52224
	ds_read_b128 v[172:175], v159 offset:53248
	ds_read_b128 v[180:183], v159 offset:54272
	ds_read_b128 v[184:187], v159 offset:55296
	ds_read_b128 v[188:191], v159 offset:56320
	global_load_lds_dwordx4 v178, s[100:101] offset:128
	s_add_i32 m0, s57, 0xffffff80
	s_nop 0
	global_load_lds_dwordx4 v144, s[100:101] offset:128
	s_barrier
	s_waitcnt lgkmcnt(0)
	v_mfma_f32_16x16x32_bf16 v[60:63], v[128:131], v[150:153], v[60:63]
	v_mfma_f32_16x16x32_bf16 v[56:59], v[136:139], v[150:153], v[56:59]
	v_mfma_f32_16x16x32_bf16 v[44:47], v[128:131], v[164:167], v[44:47]
	v_mfma_f32_16x16x32_bf16 v[40:43], v[136:139], v[164:167], v[40:43]
	v_mfma_f32_16x16x32_bf16 v[28:31], v[128:131], v[172:175], v[28:31]
	v_mfma_f32_16x16x32_bf16 v[24:27], v[136:139], v[172:175], v[24:27]
	v_mfma_f32_16x16x32_bf16 v[12:15], v[128:131], v[184:187], v[12:15]
	v_mfma_f32_16x16x32_bf16 v[8:11], v[136:139], v[184:187], v[8:11]
	v_mfma_f32_16x16x32_bf16 v[60:63], v[132:135], v[160:163], v[60:63]
	v_mfma_f32_16x16x32_bf16 v[56:59], v[140:143], v[160:163], v[56:59]
	v_mfma_f32_16x16x32_bf16 v[44:47], v[132:135], v[168:171], v[44:47]
	v_mfma_f32_16x16x32_bf16 v[40:43], v[140:143], v[168:171], v[40:43]
	v_mfma_f32_16x16x32_bf16 v[28:31], v[132:135], v[180:183], v[28:31]
	v_mfma_f32_16x16x32_bf16 v[24:27], v[140:143], v[180:183], v[24:27]
	v_mfma_f32_16x16x32_bf16 v[12:15], v[132:135], v[188:191], v[12:15]
	v_mfma_f32_16x16x32_bf16 v[8:11], v[140:143], v[188:191], v[8:11]
	s_barrier
	s_add_u32 s16, s20, 0x80080
	s_addc_u32 s17, s21, 0
	s_add_i32 s20, s22, s28
	s_mov_b32 m0, s20
	s_nop 0
	global_load_lds_dwordx4 v178, s[16:17]
	s_add_i32 m0, s20, 0x2000
	s_nop 0
	global_load_lds_dwordx4 v144, s[16:17]
	s_waitcnt vmcnt(6)
	s_barrier
	v_mfma_f32_16x16x32_bf16 v[52:55], v[192:195], v[150:153], v[52:55]
	v_mfma_f32_16x16x32_bf16 v[48:51], v[204:207], v[150:153], v[48:51]
	v_mfma_f32_16x16x32_bf16 v[36:39], v[192:195], v[164:167], v[36:39]
	v_mfma_f32_16x16x32_bf16 v[32:35], v[204:207], v[164:167], v[32:35]
	v_mfma_f32_16x16x32_bf16 v[20:23], v[192:195], v[172:175], v[20:23]
	v_mfma_f32_16x16x32_bf16 v[16:19], v[204:207], v[172:175], v[16:19]
	v_mfma_f32_16x16x32_bf16 v[4:7], v[192:195], v[184:187], v[4:7]
	v_mfma_f32_16x16x32_bf16 v[0:3], v[204:207], v[184:187], v[0:3]
	v_mfma_f32_16x16x32_bf16 v[52:55], v[196:199], v[160:163], v[52:55]
	v_mfma_f32_16x16x32_bf16 v[48:51], v[212:215], v[160:163], v[48:51]
	v_mfma_f32_16x16x32_bf16 v[36:39], v[196:199], v[168:171], v[36:39]
	v_mfma_f32_16x16x32_bf16 v[32:35], v[212:215], v[168:171], v[32:35]
	v_mfma_f32_16x16x32_bf16 v[20:23], v[196:199], v[180:183], v[20:23]
	v_mfma_f32_16x16x32_bf16 v[16:19], v[212:215], v[180:183], v[16:19]
	v_mfma_f32_16x16x32_bf16 v[4:7], v[196:199], v[188:191], v[4:7]
	v_mfma_f32_16x16x32_bf16 v[0:3], v[212:215], v[188:191], v[0:3]
	s_add_i32 s63, s63, 2
	s_add_u32 s5, s5, 0x100
	s_addc_u32 s62, s62, 0
	s_cmp_gt_u32 s63, 29
	s_mov_b64 s[16:17], s[18:19]
	s_barrier
	s_cbranch_scc0 .LBB0_1077
	s_lshl_b32 s5, s60, 8
	s_add_i32 s12, s5, 0xfffff000
	s_ashr_i32 s12, s12, 11
	s_add_i32 s12, s12, 1
	s_cmp_lt_i32 s60, 16
	s_cselect_b32 s12, 0, s12
	v_add_u32_e32 v154, s5, v156
	v_lshl_or_b32 v152, s61, 8, v158
	s_mul_hi_i32 s15, s12, 0xc000
	s_mul_i32 s14, s12, 0xc000
	v_readlane_b32 s12, v254, 59
	v_readlane_b32 s13, v254, 63
	v_ashrrev_i32_e32 v155, 31, v154
	s_cselect_b32 s13, s12, s13
	v_readlane_b32 s12, v254, 61
	v_readlane_b32 s16, v255, 1
	v_ashrrev_i32_e32 v153, 31, v152
	v_lshlrev_b64 v[150:151], 11, v[154:155]
	s_cselect_b32 s12, s12, s16
	s_add_u32 s14, s35, s14
	v_lshl_add_u64 v[150:151], v[150:151], 0, v[152:153]
	s_addc_u32 s15, s39, s15
	v_lshlrev_b64 v[150:151], 2, v[150:151]
	v_lshl_add_u64 v[128:129], v[152:153], 2, s[14:15]
	v_lshl_add_u64 v[166:167], s[12:13], 0, v[150:151]
	global_load_dwordx4 v[140:143], v[128:129], off
	global_load_dwordx4 v[136:139], v[128:129], off offset:64
	global_load_dwordx4 v[132:135], v[128:129], off offset:512
	s_nop 0
	global_load_dwordx4 v[128:131], v[128:129], off offset:576
	v_readlane_b32 s68, v252, 37
	v_readlane_b32 s82, v252, 51
	v_readlane_b32 s83, v252, 52
	s_and_b64 vcc, exec, s[10:11]
	s_mov_b32 s61, s59
	s_mov_b32 s60, s4
	s_mov_b64 s[18:19], s[6:7]
	s_mov_b64 s[16:17], s[8:9]
	v_readlane_b32 s69, v252, 38
	v_readlane_b32 s70, v252, 39
	v_readlane_b32 s71, v252, 40
	v_readlane_b32 s72, v252, 41
	v_readlane_b32 s73, v252, 42
	v_readlane_b32 s74, v252, 43
	v_readlane_b32 s75, v252, 44
	v_readlane_b32 s76, v252, 45
	v_readlane_b32 s77, v252, 46
	v_readlane_b32 s78, v252, 47
	v_readlane_b32 s79, v252, 48
	v_readlane_b32 s80, v252, 49
	v_readlane_b32 s81, v252, 50
	s_nop 4
	v_mov_b32_e32 v145, v150
	v_add_u32_e32 v164, 0x20000, v145
	v_add_u32_e32 v165, 0x40000, v145
	v_add_u32_e32 v176, 0x60000, v145
	v_add_u32_e32 v177, 0x100000, v145
	v_add_u32_e32 v223, 0x120000, v145
	v_add_u32_e32 v248, 0x140000, v145
	v_add_u32_e32 v249, 0x160000, v145
	global_load_dwordx4 v[160:163], v145, s[12:13]
	global_load_dwordx4 v[168:171], v145, s[12:13] offset:64
	global_load_dwordx4 v[172:175], v145, s[12:13] offset:512
	global_load_dwordx4 v[180:183], v145, s[12:13] offset:576
	global_load_dwordx4 v[184:187], v164, s[12:13]
	global_load_dwordx4 v[188:191], v164, s[12:13] offset:64
	global_load_dwordx4 v[192:195], v164, s[12:13] offset:512
	global_load_dwordx4 v[196:199], v164, s[12:13] offset:576
	global_load_dwordx4 v[204:207], v165, s[12:13]
	global_load_dwordx4 v[212:215], v165, s[12:13] offset:64
	global_load_dwordx4 v[224:227], v165, s[12:13] offset:512
	global_load_dwordx4 v[228:231], v165, s[12:13] offset:576
	global_load_dwordx4 v[232:235], v176, s[12:13]
	global_load_dwordx4 v[236:239], v176, s[12:13] offset:64
	global_load_dwordx4 v[240:243], v176, s[12:13] offset:512
	global_load_dwordx4 v[244:247], v176, s[12:13] offset:576
	s_waitcnt vmcnt(15)
	v_pk_fma_f32 v[126:127], v[126:127], v[142:143], v[162:163]
	v_pk_fma_f32 v[124:125], v[124:125], v[140:141], v[160:161]
	global_store_dwordx4 v145, v[124:127], s[82:83]
	global_load_dwordx4 v[160:163], v177, s[12:13]
	s_waitcnt vmcnt(16)
	v_pk_fma_f32 v[122:123], v[122:123], v[138:139], v[170:171]
	v_pk_fma_f32 v[120:121], v[120:121], v[136:137], v[168:169]
	global_store_dwordx4 v145, v[120:123], s[82:83] offset:64
	global_load_dwordx4 v[168:171], v177, s[12:13] offset:64
	s_waitcnt vmcnt(17)
	v_pk_fma_f32 v[118:119], v[118:119], v[134:135], v[174:175]
	v_pk_fma_f32 v[116:117], v[116:117], v[132:133], v[172:173]
	global_store_dwordx4 v145, v[116:119], s[82:83] offset:512
	global_load_dwordx4 v[172:175], v177, s[12:13] offset:512
	s_waitcnt vmcnt(18)
	v_pk_fma_f32 v[114:115], v[114:115], v[130:131], v[182:183]
	v_pk_fma_f32 v[112:113], v[112:113], v[128:129], v[180:181]
	global_store_dwordx4 v145, v[112:115], s[82:83] offset:576
	global_load_dwordx4 v[180:183], v177, s[12:13] offset:576
	s_waitcnt vmcnt(19)
	v_pk_fma_f32 v[110:111], v[110:111], v[142:143], v[186:187]
	v_pk_fma_f32 v[108:109], v[108:109], v[140:141], v[184:185]
	global_store_dwordx4 v164, v[108:111], s[82:83]
	global_load_dwordx4 v[184:187], v223, s[12:13]
	s_waitcnt vmcnt(20)
	v_pk_fma_f32 v[106:107], v[106:107], v[138:139], v[190:191]
	v_pk_fma_f32 v[104:105], v[104:105], v[136:137], v[188:189]
	global_store_dwordx4 v164, v[104:107], s[82:83] offset:64
	global_load_dwordx4 v[188:191], v223, s[12:13] offset:64
	s_waitcnt vmcnt(21)
	v_pk_fma_f32 v[102:103], v[102:103], v[134:135], v[194:195]
	v_pk_fma_f32 v[100:101], v[100:101], v[132:133], v[192:193]
	global_store_dwordx4 v164, v[100:103], s[82:83] offset:512
	global_load_dwordx4 v[192:195], v223, s[12:13] offset:512
	s_waitcnt vmcnt(22)
	v_pk_fma_f32 v[98:99], v[98:99], v[130:131], v[198:199]
	v_pk_fma_f32 v[96:97], v[96:97], v[128:129], v[196:197]
	global_store_dwordx4 v164, v[96:99], s[82:83] offset:576
	global_load_dwordx4 v[196:199], v223, s[12:13] offset:576
	s_waitcnt vmcnt(23)
	v_pk_fma_f32 v[94:95], v[94:95], v[142:143], v[206:207]
	v_pk_fma_f32 v[92:93], v[92:93], v[140:141], v[204:205]
	global_store_dwordx4 v165, v[92:95], s[82:83]
	global_load_dwordx4 v[204:207], v248, s[12:13]
	s_waitcnt vmcnt(24)
	v_pk_fma_f32 v[90:91], v[90:91], v[138:139], v[214:215]
	v_pk_fma_f32 v[88:89], v[88:89], v[136:137], v[212:213]
	global_store_dwordx4 v165, v[88:91], s[82:83] offset:64
	global_load_dwordx4 v[212:215], v248, s[12:13] offset:64
	s_waitcnt vmcnt(25)
	v_pk_fma_f32 v[86:87], v[86:87], v[134:135], v[226:227]
	v_pk_fma_f32 v[84:85], v[84:85], v[132:133], v[224:225]
	global_store_dwordx4 v165, v[84:87], s[82:83] offset:512
	global_load_dwordx4 v[224:227], v248, s[12:13] offset:512
	s_waitcnt vmcnt(26)
	v_pk_fma_f32 v[82:83], v[82:83], v[130:131], v[230:231]
	v_pk_fma_f32 v[80:81], v[80:81], v[128:129], v[228:229]
	global_store_dwordx4 v165, v[80:83], s[82:83] offset:576
	global_load_dwordx4 v[228:231], v248, s[12:13] offset:576
	s_waitcnt vmcnt(27)
	v_pk_fma_f32 v[78:79], v[78:79], v[142:143], v[234:235]
	v_pk_fma_f32 v[76:77], v[76:77], v[140:141], v[232:233]
	global_store_dwordx4 v176, v[76:79], s[82:83]
	global_load_dwordx4 v[232:235], v249, s[12:13]
	s_waitcnt vmcnt(28)
	v_pk_fma_f32 v[74:75], v[74:75], v[138:139], v[238:239]
	v_pk_fma_f32 v[72:73], v[72:73], v[136:137], v[236:237]
	global_store_dwordx4 v176, v[72:75], s[82:83] offset:64
	global_load_dwordx4 v[236:239], v249, s[12:13] offset:64
	s_waitcnt vmcnt(29)
	v_pk_fma_f32 v[70:71], v[70:71], v[134:135], v[242:243]
	v_pk_fma_f32 v[68:69], v[68:69], v[132:133], v[240:241]
	global_store_dwordx4 v176, v[68:71], s[82:83] offset:512
	global_load_dwordx4 v[240:243], v249, s[12:13] offset:512
	s_waitcnt vmcnt(30)
	v_pk_fma_f32 v[66:67], v[66:67], v[130:131], v[246:247]
	v_pk_fma_f32 v[64:65], v[64:65], v[128:129], v[244:245]
	global_store_dwordx4 v176, v[64:67], s[82:83] offset:576
	global_load_dwordx4 v[244:247], v249, s[12:13] offset:576
	s_waitcnt vmcnt(30)
	v_pk_fma_f32 v[62:63], v[62:63], v[142:143], v[162:163]
	v_pk_fma_f32 v[60:61], v[60:61], v[140:141], v[160:161]
	global_store_dwordx4 v177, v[60:63], s[82:83]
	s_waitcnt vmcnt(29)
	v_pk_fma_f32 v[58:59], v[58:59], v[138:139], v[170:171]
	v_pk_fma_f32 v[56:57], v[56:57], v[136:137], v[168:169]
	global_store_dwordx4 v177, v[56:59], s[82:83] offset:64
	s_waitcnt vmcnt(28)
	v_pk_fma_f32 v[54:55], v[54:55], v[134:135], v[174:175]
	v_pk_fma_f32 v[52:53], v[52:53], v[132:133], v[172:173]
	global_store_dwordx4 v177, v[52:55], s[82:83] offset:512
	s_waitcnt vmcnt(27)
	v_pk_fma_f32 v[50:51], v[50:51], v[130:131], v[182:183]
	v_pk_fma_f32 v[48:49], v[48:49], v[128:129], v[180:181]
	global_store_dwordx4 v177, v[48:51], s[82:83] offset:576
	s_waitcnt vmcnt(26)
	v_pk_fma_f32 v[46:47], v[46:47], v[142:143], v[186:187]
	v_pk_fma_f32 v[44:45], v[44:45], v[140:141], v[184:185]
	global_store_dwordx4 v223, v[44:47], s[82:83]
	s_waitcnt vmcnt(25)
	v_pk_fma_f32 v[42:43], v[42:43], v[138:139], v[190:191]
	v_pk_fma_f32 v[40:41], v[40:41], v[136:137], v[188:189]
	global_store_dwordx4 v223, v[40:43], s[82:83] offset:64
	s_waitcnt vmcnt(24)
	v_pk_fma_f32 v[38:39], v[38:39], v[134:135], v[194:195]
	v_pk_fma_f32 v[36:37], v[36:37], v[132:133], v[192:193]
	global_store_dwordx4 v223, v[36:39], s[82:83] offset:512
	s_waitcnt vmcnt(23)
	v_pk_fma_f32 v[34:35], v[34:35], v[130:131], v[198:199]
	v_pk_fma_f32 v[32:33], v[32:33], v[128:129], v[196:197]
	global_store_dwordx4 v223, v[32:35], s[82:83] offset:576
	s_waitcnt vmcnt(22)
	v_pk_fma_f32 v[30:31], v[30:31], v[142:143], v[206:207]
	v_pk_fma_f32 v[28:29], v[28:29], v[140:141], v[204:205]
	global_store_dwordx4 v248, v[28:31], s[82:83]
	s_waitcnt vmcnt(21)
	v_pk_fma_f32 v[26:27], v[26:27], v[138:139], v[214:215]
	v_pk_fma_f32 v[24:25], v[24:25], v[136:137], v[212:213]
	global_store_dwordx4 v248, v[24:27], s[82:83] offset:64
	s_waitcnt vmcnt(20)
	v_pk_fma_f32 v[22:23], v[22:23], v[134:135], v[226:227]
	v_pk_fma_f32 v[20:21], v[20:21], v[132:133], v[224:225]
	global_store_dwordx4 v248, v[20:23], s[82:83] offset:512
	s_waitcnt vmcnt(19)
	v_pk_fma_f32 v[18:19], v[18:19], v[130:131], v[230:231]
	v_pk_fma_f32 v[16:17], v[16:17], v[128:129], v[228:229]
	global_store_dwordx4 v248, v[16:19], s[82:83] offset:576
	s_waitcnt vmcnt(18)
	v_pk_fma_f32 v[14:15], v[14:15], v[142:143], v[234:235]
	v_pk_fma_f32 v[12:13], v[12:13], v[140:141], v[232:233]
	global_store_dwordx4 v249, v[12:15], s[82:83]
	s_waitcnt vmcnt(17)
	v_pk_fma_f32 v[10:11], v[10:11], v[138:139], v[238:239]
	v_pk_fma_f32 v[8:9], v[8:9], v[136:137], v[236:237]
	global_store_dwordx4 v249, v[8:11], s[82:83] offset:64
	s_waitcnt vmcnt(16)
	v_pk_fma_f32 v[6:7], v[6:7], v[134:135], v[242:243]
	v_pk_fma_f32 v[4:5], v[4:5], v[132:133], v[240:241]
	global_store_dwordx4 v249, v[4:7], s[82:83] offset:512
	s_waitcnt vmcnt(15)
	v_pk_fma_f32 v[2:3], v[2:3], v[130:131], v[246:247]
	v_pk_fma_f32 v[0:1], v[0:1], v[128:129], v[244:245]
	global_store_dwordx4 v249, v[0:3], s[82:83] offset:576
	s_mov_b64 s[14:15], 0x160000
	s_cbranch_vccz .LBB0_1074
	s_waitcnt vmcnt(0)
	s_mov_b32 s4, s86
	s_cmp_gt_u32 s4, 3
	s_mov_b32 s34, 0x10000
	s_movk_i32 s57, 0x404
	s_cbranch_scc1 .LBB0_1081
	s_barrier

.LBB0_1193:
	s_add_u32 s12, s88, 0x1ebdb700
	s_addc_u32 s13, s89, 0
	s_add_u32 s17, s88, 0x114db700
	v_bfe_u32 v224, v12, 4, 2
	s_addc_u32 s18, s89, 0
	v_readlane_b32 s16, v255, 8
	v_and_b32_e32 v223, 15, v12
	s_lshl_b32 s14, s5, 6
	v_lshlrev_b32_e32 v15, 4, v224
	v_lshlrev_b32_e32 v12, 2, v12
	s_and_b32 s7, s16, 3
	v_writelane_b32 v255, s14, 9
	v_lshl_or_b32 v15, v223, 6, v15
	s_lshl_b32 s14, s5, 13
	v_and_b32_e32 v12, 32, v12
	s_add_i32 m0, s84, 0x18000
	v_lshl_add_u64 v[6:7], v[6:7], 0, s[54:55]
	v_bitop3_b32 v16, v15, s14, v12 bitop3:0xde
	s_lshl_b32 s22, s7, 5
	s_lshl_b32 s14, s7, 12
	s_waitcnt vmcnt(4)
	s_barrier
	global_load_lds_dwordx4 v[6:7], off
	v_lshl_add_u64 v[4:5], v[4:5], 0, s[54:55]
	s_add_i32 m0, s84, 0x1a000
	s_add_i32 s59, s84, 0x8000
	s_add_i32 s20, s84, 0xa000
	v_bitop3_b32 v225, v15, s14, v12 bitop3:0xde
	global_load_lds_dwordx4 v[4:5], off
	v_lshl_add_u64 v[2:3], v[2:3], 0, s[54:55]
	s_mov_b32 m0, s59
	s_add_u32 s14, s66, 0x80080
	global_load_lds_dwordx4 v[2:3], off
	v_lshl_add_u64 v[0:1], v[0:1], 0, s[54:55]
	s_mov_b32 m0, s20
	s_addc_u32 s15, s67, 0
	global_load_lds_dwordx4 v[0:1], off
	s_add_i32 m0, s84, 0x1c000
	s_nop 0
	global_load_lds_dwordx4 v182, s[14:15]
	s_add_i32 m0, s84, 0x1e000
	s_lshl_b32 s5, s5, 11
	global_load_lds_dwordx4 v186, s[14:15]
	s_lshl_b32 s34, s7, 9
	s_xor_b64 s[14:15], s[10:11], -1
	s_cmp_gt_u32 s16, 3
	s_cselect_b64 s[26:27], -1, 0
	v_writelane_b32 v255, s26, 12
	s_cmp_lt_u32 s16, 4
	v_cndmask_b32_e64 v1, 0, 1, s[14:15]
	v_writelane_b32 v255, s27, 13
	s_cselect_b64 s[26:27], -1, 0
	v_cndmask_b32_e64 v0, 0, 1, s[26:27]
	v_writelane_b32 v255, s26, 14
	s_and_b64 s[14:15], s[26:27], exec
	s_cselect_b32 s14, 0, 2
	s_movk_i32 s15, 0x1800
	v_readfirstlane_b32 s19, v0
	s_cselect_b32 s15, s15, 0x1000
	s_or_b32 s14, s14, s19
	v_readfirstlane_b32 s19, v1
	s_or_b32 s6, s6, s19
	s_lshl_b32 s14, s14, 11
	s_lshl_b32 s6, s6, 11
	s_lshl_b32 s7, s7, 7
	v_writelane_b32 v255, s27, 15
	s_add_u32 s16, s17, s7
	v_writelane_b32 v255, s17, 4
	s_addc_u32 s17, s18, 0
	s_add_i32 s7, 0, 0x20000
	v_writelane_b32 v255, s18, 22
	s_add_i32 s19, s7, s5
	s_add_i32 s5, s5, 0
	v_writelane_b32 v255, s16, 23
	s_add_i32 s5, s5, s34
	s_add_i32 s5, s5, 0x21000
	v_writelane_b32 v255, s17, 24
	s_add_i32 s16, s19, s34
	v_writelane_b32 v255, s16, 16
	s_add_u32 s16, s60, 0xac00
	s_addc_u32 s17, s61, 0
	v_writelane_b32 v255, s5, 7
	s_add_u32 s64, s60, 0x15800
	v_writelane_b32 v255, s16, 18
	s_addc_u32 s65, s61, 0
	v_lshlrev_b32_e32 v0, 15, v11
	v_writelane_b32 v255, s17, 19
	s_add_u32 s16, s60, 0x5600
	s_addc_u32 s17, s61, 0
	v_writelane_b32 v254, s16, 59
	v_and_b32_e32 v0, 0xffff0000, v0
	v_lshl_add_u32 v0, v13, 12, v0
	v_writelane_b32 v254, s17, 60
	s_add_u32 s16, s60, 0x10200
	s_addc_u32 s17, s61, 0
	s_add_u32 s26, s60, 0x1ae00
	v_writelane_b32 v254, s16, 61
	s_addc_u32 s27, s61, 0
	s_add_u32 s30, s80, 0x5600
	v_writelane_b32 v254, s17, 62
	s_addc_u32 s31, s81, 0
	v_readlane_b32 s68, v254, 40
	v_readlane_b32 s69, v254, 41
	v_readlane_b32 s70, v254, 42
	v_readlane_b32 s71, v254, 43
	v_readlane_b32 s72, v254, 44
	v_readlane_b32 s73, v254, 45
	v_readlane_b32 s74, v254, 46
	v_readlane_b32 s75, v254, 47
	v_readlane_b32 s76, v254, 48
	v_readlane_b32 s77, v254, 49
	v_readlane_b32 s78, v254, 50
	v_readlane_b32 s79, v254, 51
	v_readlane_b32 s80, v254, 52
	v_readlane_b32 s81, v254, 53
	v_readlane_b32 s82, v254, 54
	v_readlane_b32 s83, v254, 55
	s_lshl_b32 s68, s22, 2
	v_writelane_b32 v254, s68, 40
	v_and_b32_e32 v1, 1, v11
	v_lshl_or_b32 v0, v1, 6, v0
	v_writelane_b32 v254, s69, 41
	v_writelane_b32 v254, s70, 42
	v_writelane_b32 v254, s71, 43
	v_writelane_b32 v254, s72, 44
	v_writelane_b32 v254, s73, 45
	v_writelane_b32 v254, s74, 46
	v_writelane_b32 v254, s75, 47
	v_writelane_b32 v254, s76, 48
	v_writelane_b32 v254, s77, 49
	v_writelane_b32 v254, s78, 50
	v_writelane_b32 v254, s79, 51
	v_writelane_b32 v254, s80, 52
	v_lshl_add_u32 v188, v14, 1, v0
	v_lshlrev_b32_e32 v0, 15, v8
	v_writelane_b32 v254, s81, 53
	v_and_b32_e32 v0, 0xffff0000, v0
	v_writelane_b32 v254, s82, 54
	s_waitcnt vmcnt(6)
	v_lshl_add_u32 v0, v9, 12, v0
	v_and_b32_e32 v1, 1, v8
	v_writelane_b32 v254, s83, 55
	s_add_i32 s19, s7, s4
	s_add_i32 s57, s7, s14
	s_add_i32 s14, s7, s6
	s_add_i32 s15, s7, s15
	v_lshl_or_b32 v0, v1, 6, v0
	v_readlane_b32 s80, v254, 63
	s_add_i32 s19, s19, s34
	s_add_i32 s57, s57, s34
	s_add_i32 s14, s14, s34
	s_add_i32 s15, s15, s34
	v_mov_b32_e32 v189, v179
	v_lshl_add_u32 v190, v10, 1, v0
	v_mov_b32_e32 v191, v179
	v_add_u32_e32 v226, 0, v16
	s_mov_b32 s21, s22
	v_readlane_b32 s81, v255, 0
	s_barrier
	s_branch .LBB0_1195

.LBB0_1198:
	s_add_u32 s70, s8, 0xfff80080
	s_addc_u32 s71, s9, -1
	s_add_i32 s77, 0, 0x10000
	v_add_u32_e32 v140, s77, v225
	ds_read_b128 v[128:131], v140
	ds_read_b128 v[132:135], v140 offset:1024
	ds_read_b128 v[136:139], v140 offset:2048
	ds_read_b128 v[140:143], v140 offset:3072
	s_cmp_eq_u32 s76, 28
	s_cselect_b32 s73, s5, s71
	s_cselect_b32 s72, s4, s70
	s_cselect_b32 s71, s7, s75
	s_cselect_b32 s70, s6, s35
	s_add_i32 m0, s84, 0xc000
	ds_read_b128 v[144:147], v226
	ds_read_b128 v[148:151], v226 offset:1024
	ds_read_b128 v[152:155], v226 offset:2048
	ds_read_b128 v[156:159], v226 offset:3072
	ds_read_b128 v[160:163], v226 offset:4096
	ds_read_b128 v[164:167], v226 offset:5120
	ds_read_b128 v[168:171], v226 offset:6144
	ds_read_b128 v[172:175], v226 offset:7168
	global_load_lds_dwordx4 v190, s[8:9]
	s_add_i32 m0, s84, 0xe000
	s_nop 0
	global_load_lds_dwordx4 v188, s[8:9]
	s_waitcnt lgkmcnt(8)
	s_barrier
	s_waitcnt lgkmcnt(0)
	v_mfma_f32_16x16x32_bf16 v[124:127], v[128:131], v[144:147], v[124:127]
	v_mfma_f32_16x16x32_bf16 v[60:63], v[136:139], v[144:147], v[60:63]
	v_mfma_f32_16x16x32_bf16 v[116:119], v[128:131], v[152:155], v[116:119]
	v_mfma_f32_16x16x32_bf16 v[52:55], v[136:139], v[152:155], v[52:55]
	v_mfma_f32_16x16x32_bf16 v[108:111], v[128:131], v[160:163], v[108:111]
	v_mfma_f32_16x16x32_bf16 v[44:47], v[136:139], v[160:163], v[44:47]
	v_mfma_f32_16x16x32_bf16 v[100:103], v[128:131], v[168:171], v[100:103]
	v_mfma_f32_16x16x32_bf16 v[36:39], v[136:139], v[168:171], v[36:39]
	v_mfma_f32_16x16x32_bf16 v[124:127], v[132:135], v[148:151], v[124:127]
	v_mfma_f32_16x16x32_bf16 v[60:63], v[140:143], v[148:151], v[60:63]
	v_mfma_f32_16x16x32_bf16 v[116:119], v[132:135], v[156:159], v[116:119]
	v_mfma_f32_16x16x32_bf16 v[52:55], v[140:143], v[156:159], v[52:55]
	v_mfma_f32_16x16x32_bf16 v[108:111], v[132:135], v[164:167], v[108:111]
	v_mfma_f32_16x16x32_bf16 v[44:47], v[140:143], v[164:167], v[44:47]
	v_mfma_f32_16x16x32_bf16 v[100:103], v[132:135], v[172:175], v[100:103]
	v_mfma_f32_16x16x32_bf16 v[36:39], v[140:143], v[172:175], v[36:39]
	s_barrier
	s_add_i32 vcc_lo, 0, 0x14000
	v_add_u32_e32 v176, vcc_lo, v225
	s_add_i32 s77, s77, s24
	ds_read_b128 v[192:195], v176
	ds_read_b128 v[196:199], v176 offset:1024
	ds_read_b128 v[204:207], v176 offset:2048
	ds_read_b128 v[212:215], v176 offset:3072
	s_mov_b32 m0, s77
	s_nop 0
	global_load_lds_dwordx4 v182, s[70:71]
	s_add_i32 m0, s77, 0x2000
	s_nop 0
	global_load_lds_dwordx4 v186, s[70:71]
	s_barrier
	s_waitcnt lgkmcnt(0)
	v_mfma_f32_16x16x32_bf16 v[120:123], v[192:195], v[144:147], v[120:123]
	v_mfma_f32_16x16x32_bf16 v[56:59], v[204:207], v[144:147], v[56:59]
	v_mfma_f32_16x16x32_bf16 v[112:115], v[192:195], v[152:155], v[112:115]
	v_mfma_f32_16x16x32_bf16 v[48:51], v[204:207], v[152:155], v[48:51]
	v_mfma_f32_16x16x32_bf16 v[104:107], v[192:195], v[160:163], v[104:107]
	v_mfma_f32_16x16x32_bf16 v[40:43], v[204:207], v[160:163], v[40:43]
	v_mfma_f32_16x16x32_bf16 v[96:99], v[192:195], v[168:171], v[96:99]
	v_mfma_f32_16x16x32_bf16 v[32:35], v[204:207], v[168:171], v[32:35]
	v_mfma_f32_16x16x32_bf16 v[120:123], v[196:199], v[148:151], v[120:123]
	v_mfma_f32_16x16x32_bf16 v[56:59], v[212:215], v[148:151], v[56:59]
	v_mfma_f32_16x16x32_bf16 v[112:115], v[196:199], v[156:159], v[112:115]
	v_mfma_f32_16x16x32_bf16 v[48:51], v[212:215], v[156:159], v[48:51]
	v_mfma_f32_16x16x32_bf16 v[104:107], v[196:199], v[164:167], v[104:107]
	v_mfma_f32_16x16x32_bf16 v[40:43], v[212:215], v[164:167], v[40:43]
	v_mfma_f32_16x16x32_bf16 v[96:99], v[196:199], v[172:175], v[96:99]
	v_mfma_f32_16x16x32_bf16 v[32:35], v[212:215], v[172:175], v[32:35]
	s_mov_b32 m0, s84
	s_mov_b64 s[100:101], s[72:73]
	s_barrier
	ds_read_b128 v[144:147], v226 offset:16384
	ds_read_b128 v[148:151], v226 offset:17408
	ds_read_b128 v[152:155], v226 offset:18432
	ds_read_b128 v[156:159], v226 offset:19456
	ds_read_b128 v[160:163], v226 offset:20480
	ds_read_b128 v[164:167], v226 offset:21504
	ds_read_b128 v[168:171], v226 offset:22528
	ds_read_b128 v[172:175], v226 offset:23552
	global_load_lds_dwordx4 v180, s[72:73]
	s_mov_b64 s[100:101], s[72:73]
	s_mov_b32 m0, s85
	s_nop 0
	global_load_lds_dwordx4 v184, s[72:73]
	s_barrier
	s_waitcnt lgkmcnt(0)
	v_mfma_f32_16x16x32_bf16 v[92:95], v[128:131], v[144:147], v[92:95]
	v_mfma_f32_16x16x32_bf16 v[28:31], v[136:139], v[144:147], v[28:31]
	v_mfma_f32_16x16x32_bf16 v[84:87], v[128:131], v[152:155], v[84:87]
	v_mfma_f32_16x16x32_bf16 v[20:23], v[136:139], v[152:155], v[20:23]
	v_mfma_f32_16x16x32_bf16 v[76:79], v[128:131], v[160:163], v[76:79]
	v_mfma_f32_16x16x32_bf16 v[12:15], v[136:139], v[160:163], v[12:15]
	v_mfma_f32_16x16x32_bf16 v[68:71], v[128:131], v[168:171], v[68:71]
	v_mfma_f32_16x16x32_bf16 v[4:7], v[136:139], v[168:171], v[4:7]
	v_mfma_f32_16x16x32_bf16 v[92:95], v[132:135], v[148:151], v[92:95]
	v_mfma_f32_16x16x32_bf16 v[28:31], v[140:143], v[148:151], v[28:31]
	v_mfma_f32_16x16x32_bf16 v[84:87], v[132:135], v[156:159], v[84:87]
	v_mfma_f32_16x16x32_bf16 v[20:23], v[140:143], v[156:159], v[20:23]
	v_mfma_f32_16x16x32_bf16 v[76:79], v[132:135], v[164:167], v[76:79]
	v_mfma_f32_16x16x32_bf16 v[12:15], v[140:143], v[164:167], v[12:15]
	v_mfma_f32_16x16x32_bf16 v[68:71], v[132:135], v[172:175], v[68:71]
	v_mfma_f32_16x16x32_bf16 v[4:7], v[140:143], v[172:175], v[4:7]
	s_barrier
	s_add_u32 s78, s70, 0x80000
	s_addc_u32 s79, s71, 0
	s_add_i32 s77, vcc_lo, s24
	s_mov_b32 m0, s77
	s_nop 0
	global_load_lds_dwordx4 v182, s[78:79]
	s_add_i32 m0, s77, 0x2000
	s_nop 0
	global_load_lds_dwordx4 v186, s[78:79]
	s_waitcnt vmcnt(6)
	s_barrier
	v_mfma_f32_16x16x32_bf16 v[88:91], v[192:195], v[144:147], v[88:91]
	v_mfma_f32_16x16x32_bf16 v[24:27], v[204:207], v[144:147], v[24:27]
	v_mfma_f32_16x16x32_bf16 v[80:83], v[192:195], v[152:155], v[80:83]
	v_mfma_f32_16x16x32_bf16 v[16:19], v[204:207], v[152:155], v[16:19]
	v_mfma_f32_16x16x32_bf16 v[72:75], v[192:195], v[160:163], v[72:75]
	v_mfma_f32_16x16x32_bf16 v[8:11], v[204:207], v[160:163], v[8:11]
	v_mfma_f32_16x16x32_bf16 v[64:67], v[192:195], v[168:171], v[64:67]
	v_mfma_f32_16x16x32_bf16 v[0:3], v[204:207], v[168:171], v[0:3]
	v_mfma_f32_16x16x32_bf16 v[88:91], v[196:199], v[148:151], v[88:91]
	v_mfma_f32_16x16x32_bf16 v[24:27], v[212:215], v[148:151], v[24:27]
	v_mfma_f32_16x16x32_bf16 v[80:83], v[196:199], v[156:159], v[80:83]
	v_mfma_f32_16x16x32_bf16 v[16:19], v[212:215], v[156:159], v[16:19]
	v_mfma_f32_16x16x32_bf16 v[72:75], v[196:199], v[164:167], v[72:75]
	v_mfma_f32_16x16x32_bf16 v[8:11], v[212:215], v[164:167], v[8:11]
	v_mfma_f32_16x16x32_bf16 v[64:67], v[196:199], v[172:175], v[64:67]
	v_mfma_f32_16x16x32_bf16 v[0:3], v[212:215], v[172:175], v[0:3]
	s_add_i32 s77, 0, 0x18000
	v_add_u32_e32 v140, s77, v225
	s_barrier
	ds_read_b128 v[128:131], v140
	ds_read_b128 v[132:135], v140 offset:1024
	ds_read_b128 v[136:139], v140 offset:2048
	ds_read_b128 v[140:143], v140 offset:3072
	s_add_u32 s72, s72, 0x80000
	s_addc_u32 s73, s73, 0
	s_mov_b32 m0, s86
	ds_read_b128 v[144:147], v226 offset:32768
	ds_read_b128 v[148:151], v226 offset:33792
	ds_read_b128 v[152:155], v226 offset:34816
	ds_read_b128 v[156:159], v226 offset:35840
	ds_read_b128 v[160:163], v226 offset:36864
	ds_read_b128 v[164:167], v226 offset:37888
	ds_read_b128 v[168:171], v226 offset:38912
	ds_read_b128 v[172:175], v226 offset:39936
	global_load_lds_dwordx4 v180, s[72:73]
	s_mov_b32 m0, s87
	s_nop 0
	global_load_lds_dwordx4 v184, s[72:73]
	s_waitcnt lgkmcnt(8)
	s_barrier
	s_waitcnt lgkmcnt(0)
	v_mfma_f32_16x16x32_bf16 v[124:127], v[128:131], v[144:147], v[124:127]
	v_mfma_f32_16x16x32_bf16 v[60:63], v[136:139], v[144:147], v[60:63]
	v_mfma_f32_16x16x32_bf16 v[116:119], v[128:131], v[152:155], v[116:119]
	v_mfma_f32_16x16x32_bf16 v[52:55], v[136:139], v[152:155], v[52:55]
	v_mfma_f32_16x16x32_bf16 v[108:111], v[128:131], v[160:163], v[108:111]
	v_mfma_f32_16x16x32_bf16 v[44:47], v[136:139], v[160:163], v[44:47]
	v_mfma_f32_16x16x32_bf16 v[100:103], v[128:131], v[168:171], v[100:103]
	v_mfma_f32_16x16x32_bf16 v[36:39], v[136:139], v[168:171], v[36:39]
	v_mfma_f32_16x16x32_bf16 v[124:127], v[132:135], v[148:151], v[124:127]
	v_mfma_f32_16x16x32_bf16 v[60:63], v[140:143], v[148:151], v[60:63]
	v_mfma_f32_16x16x32_bf16 v[116:119], v[132:135], v[156:159], v[116:119]
	v_mfma_f32_16x16x32_bf16 v[52:55], v[140:143], v[156:159], v[52:55]
	v_mfma_f32_16x16x32_bf16 v[108:111], v[132:135], v[164:167], v[108:111]
	v_mfma_f32_16x16x32_bf16 v[44:47], v[140:143], v[164:167], v[44:47]
	v_mfma_f32_16x16x32_bf16 v[100:103], v[132:135], v[172:175], v[100:103]
	v_mfma_f32_16x16x32_bf16 v[36:39], v[140:143], v[172:175], v[36:39]
	s_barrier
	s_add_i32 s72, 0, 0x1c000
	s_add_i32 s73, s77, s24
	v_add_u32_e32 v178, s72, v225
	s_add_i32 m0, s73, 0xffffff80
	ds_read_b128 v[192:195], v178
	ds_read_b128 v[196:199], v178 offset:1024
	ds_read_b128 v[204:207], v178 offset:2048
	ds_read_b128 v[212:215], v178 offset:3072
	global_load_lds_dwordx4 v182, s[70:71] offset:128
	s_add_i32 m0, s73, 0x1f80
	s_nop 0
	global_load_lds_dwordx4 v186, s[70:71] offset:128
	s_barrier
	s_waitcnt lgkmcnt(0)
	v_mfma_f32_16x16x32_bf16 v[120:123], v[192:195], v[144:147], v[120:123]
	v_mfma_f32_16x16x32_bf16 v[56:59], v[204:207], v[144:147], v[56:59]
	v_mfma_f32_16x16x32_bf16 v[112:115], v[192:195], v[152:155], v[112:115]
	v_mfma_f32_16x16x32_bf16 v[48:51], v[204:207], v[152:155], v[48:51]
	v_mfma_f32_16x16x32_bf16 v[104:107], v[192:195], v[160:163], v[104:107]
	v_mfma_f32_16x16x32_bf16 v[40:43], v[204:207], v[160:163], v[40:43]
	v_mfma_f32_16x16x32_bf16 v[96:99], v[192:195], v[168:171], v[96:99]
	v_mfma_f32_16x16x32_bf16 v[32:35], v[204:207], v[168:171], v[32:35]
	v_mfma_f32_16x16x32_bf16 v[120:123], v[196:199], v[148:151], v[120:123]
	v_mfma_f32_16x16x32_bf16 v[56:59], v[212:215], v[148:151], v[56:59]
	v_mfma_f32_16x16x32_bf16 v[112:115], v[196:199], v[156:159], v[112:115]
	v_mfma_f32_16x16x32_bf16 v[48:51], v[212:215], v[156:159], v[48:51]
	v_mfma_f32_16x16x32_bf16 v[104:107], v[196:199], v[164:167], v[104:107]
	v_mfma_f32_16x16x32_bf16 v[40:43], v[212:215], v[164:167], v[40:43]
	v_mfma_f32_16x16x32_bf16 v[96:99], v[196:199], v[172:175], v[96:99]
	v_mfma_f32_16x16x32_bf16 v[32:35], v[212:215], v[172:175], v[32:35]
	s_add_i32 m0, s59, 0xffffff80
	s_barrier
	ds_read_b128 v[144:147], v226 offset:49152
	ds_read_b128 v[148:151], v226 offset:50176
	ds_read_b128 v[152:155], v226 offset:51200
	ds_read_b128 v[156:159], v226 offset:52224
	ds_read_b128 v[160:163], v226 offset:53248
	ds_read_b128 v[164:167], v226 offset:54272
	ds_read_b128 v[168:171], v226 offset:55296
	ds_read_b128 v[172:175], v226 offset:56320
	global_load_lds_dwordx4 v180, s[100:101] offset:128
	s_add_i32 m0, s20, 0xffffff80
	s_nop 0
	global_load_lds_dwordx4 v184, s[100:101] offset:128
	s_barrier
	s_waitcnt lgkmcnt(0)
	v_mfma_f32_16x16x32_bf16 v[92:95], v[128:131], v[144:147], v[92:95]
	v_mfma_f32_16x16x32_bf16 v[28:31], v[136:139], v[144:147], v[28:31]
	v_mfma_f32_16x16x32_bf16 v[84:87], v[128:131], v[152:155], v[84:87]
	v_mfma_f32_16x16x32_bf16 v[20:23], v[136:139], v[152:155], v[20:23]
	v_mfma_f32_16x16x32_bf16 v[76:79], v[128:131], v[160:163], v[76:79]
	v_mfma_f32_16x16x32_bf16 v[12:15], v[136:139], v[160:163], v[12:15]
	v_mfma_f32_16x16x32_bf16 v[68:71], v[128:131], v[168:171], v[68:71]
	v_mfma_f32_16x16x32_bf16 v[4:7], v[136:139], v[168:171], v[4:7]
	v_mfma_f32_16x16x32_bf16 v[92:95], v[132:135], v[148:151], v[92:95]
	v_mfma_f32_16x16x32_bf16 v[28:31], v[140:143], v[148:151], v[28:31]
	v_mfma_f32_16x16x32_bf16 v[84:87], v[132:135], v[156:159], v[84:87]
	v_mfma_f32_16x16x32_bf16 v[20:23], v[140:143], v[156:159], v[20:23]
	v_mfma_f32_16x16x32_bf16 v[76:79], v[132:135], v[164:167], v[76:79]
	v_mfma_f32_16x16x32_bf16 v[12:15], v[140:143], v[164:167], v[12:15]
	v_mfma_f32_16x16x32_bf16 v[68:71], v[132:135], v[172:175], v[68:71]
	v_mfma_f32_16x16x32_bf16 v[4:7], v[140:143], v[172:175], v[4:7]
	s_barrier
	s_add_u32 s70, s70, 0x80080
	s_addc_u32 s71, s71, 0
	s_add_i32 s72, s72, s24
	s_mov_b32 m0, s72
	s_nop 0
	global_load_lds_dwordx4 v182, s[70:71]
	s_add_i32 m0, s72, 0x2000
	s_nop 0
	global_load_lds_dwordx4 v186, s[70:71]
	s_waitcnt vmcnt(6)
	s_barrier
	v_mfma_f32_16x16x32_bf16 v[88:91], v[192:195], v[144:147], v[88:91]
	v_mfma_f32_16x16x32_bf16 v[24:27], v[204:207], v[144:147], v[24:27]
	v_mfma_f32_16x16x32_bf16 v[80:83], v[192:195], v[152:155], v[80:83]
	v_mfma_f32_16x16x32_bf16 v[16:19], v[204:207], v[152:155], v[16:19]
	v_mfma_f32_16x16x32_bf16 v[72:75], v[192:195], v[160:163], v[72:75]
	v_mfma_f32_16x16x32_bf16 v[8:11], v[204:207], v[160:163], v[8:11]
	v_mfma_f32_16x16x32_bf16 v[64:67], v[192:195], v[168:171], v[64:67]
	v_mfma_f32_16x16x32_bf16 v[0:3], v[204:207], v[168:171], v[0:3]
	v_mfma_f32_16x16x32_bf16 v[88:91], v[196:199], v[148:151], v[88:91]
	v_mfma_f32_16x16x32_bf16 v[24:27], v[212:215], v[148:151], v[24:27]
	v_mfma_f32_16x16x32_bf16 v[80:83], v[196:199], v[156:159], v[80:83]
	v_mfma_f32_16x16x32_bf16 v[16:19], v[212:215], v[156:159], v[16:19]
	v_mfma_f32_16x16x32_bf16 v[72:75], v[196:199], v[164:167], v[72:75]
	v_mfma_f32_16x16x32_bf16 v[8:11], v[212:215], v[164:167], v[8:11]
	v_mfma_f32_16x16x32_bf16 v[64:67], v[196:199], v[172:175], v[64:67]
	v_mfma_f32_16x16x32_bf16 v[0:3], v[212:215], v[172:175], v[0:3]
	s_add_i32 s76, s76, 2
	s_add_u32 s35, s35, 0x100
	s_addc_u32 s75, s75, 0
	s_add_u32 s8, s8, 0x100
	s_addc_u32 s9, s9, 0
	s_cmp_gt_u32 s76, 29
	s_barrier
	s_cbranch_scc0 .LBB0_1198
	v_mov_b32_e32 v140, v224
	v_mov_b32_e32 v194, v223
	v_readlane_b32 s4, v255, 16
	v_lshlrev_b32_e32 v227, 6, v140
	v_cmp_lt_i32_e32 vcc, 14, v194
	v_add_u32_e32 v141, s4, v227
	s_mov_b64 s[4:5], 0
	s_and_saveexec_b64 s[6:7], vcc
	s_xor_b64 s[6:7], exec, s[6:7]
	s_cbranch_execz .LBB0_1203
	v_cmp_eq_u32_e32 vcc, 15, v194
	s_and_saveexec_b64 s[8:9], vcc
	s_mov_b64 s[4:5], exec
	ds_write_b128 v141, v[100:103] offset:256
	s_or_b64 exec, exec, s[8:9]
	s_and_b64 s[4:5], s[4:5], exec

.LBB0_1359:
	v_readlane_b32 s6, v255, 20
	v_readlane_b32 s7, v255, 21
	s_lshl_b64 s[6:7], s[6:7], 2
	s_add_u32 s5, s88, s6
	s_addc_u32 s6, s89, s7
	v_bfe_u32 v18, v16, 4, 2
	s_add_u32 s35, s5, 0xc34a000
	v_and_b32_e32 v17, 15, v16
	v_lshlrev_b32_e32 v19, 4, v18
	v_lshlrev_b32_e32 v16, 2, v16
	s_addc_u32 s39, s6, 0
	v_lshl_or_b32 v152, s4, 6, v17
	v_lshl_or_b32 v17, v17, 6, v19
	s_lshl_b32 s4, s4, 13
	v_and_b32_e32 v16, 32, v16
	v_bitop3_b32 v19, v17, s4, v16 bitop3:0xde
	s_lshl_b32 s4, s86, 5
	s_and_b32 s6, s4, 0x60
	s_add_i32 m0, s29, 0x18000
	v_lshl_add_u64 v[6:7], v[6:7], 0, s[54:55]
	s_lshl_b32 s4, s6, 7
	s_waitcnt vmcnt(4)
	s_barrier
	global_load_lds_dwordx4 v[6:7], off
	v_lshl_add_u64 v[4:5], v[4:5], 0, s[54:55]
	s_add_i32 m0, s29, 0x1a000
	s_add_i32 s56, s29, 0x8000
	s_add_i32 s57, s29, 0xa000
	v_bitop3_b32 v153, v17, s4, v16 bitop3:0xde
	global_load_lds_dwordx4 v[4:5], off
	v_lshl_add_u64 v[2:3], v[2:3], 0, s[54:55]
	s_mov_b32 m0, s56
	s_add_u32 s4, s16, 0x158080
	global_load_lds_dwordx4 v[2:3], off
	v_lshl_add_u64 v[0:1], v[0:1], 0, s[54:55]
	s_mov_b32 m0, s57
	s_addc_u32 s5, s17, 0
	global_load_lds_dwordx4 v[0:1], off
	s_add_i32 m0, s29, 0x1c000
	s_nop 0
	global_load_lds_dwordx4 v178, s[4:5]
	s_add_i32 m0, s29, 0x1e000
	v_lshl_or_b32 v154, v18, 2, s6
	global_load_lds_dwordx4 v144, s[4:5]
	s_movk_i32 s6, 0x1580
	v_lshrrev_b32_e32 v1, 1, v8
	v_mul_lo_u32 v0, v9, s6
	s_mov_b32 s7, 0x15800
	v_mad_u64_u32 v[0:1], s[4:5], v1, s7, v[0:1]
	v_or_b32_e32 v0, v0, v10
	v_add_lshl_u32 v0, v0, v11, 1
	v_mov_b32_e32 v1, v179
	s_mov_b64 s[8:9], 0x158080
	v_lshl_add_u64 v[146:147], v[0:1], 0, s[8:9]
	v_lshrrev_b32_e32 v1, 1, v12
	v_mul_lo_u32 v0, v13, s6
	v_mad_u64_u32 v[0:1], s[4:5], v1, s7, v[0:1]
	s_waitcnt vmcnt(6)
	v_or_b32_e32 v0, v0, v14
	v_add_lshl_u32 v0, v0, v15, 1
	v_mov_b32_e32 v1, v179
	v_lshl_add_u64 v[148:149], v[0:1], 0, s[8:9]
	s_mov_b32 s58, 0
	v_add_u32_e32 v155, 0, v19
	s_barrier

.LBB0_1363:
	s_add_u32 s16, s14, 0x100
	s_addc_u32 s17, s15, 0
	s_add_i32 s68, 0, 0x10000
	v_add_u32_e32 v76, s68, v153
	ds_read_b128 v[48:51], v76
	ds_read_b128 v[68:71], v76 offset:1024
	ds_read_b128 v[72:75], v76 offset:2048
	ds_read_b128 v[76:79], v76 offset:3072
	s_cmpk_eq_i32 s67, 0x52
	s_cselect_b32 s21, s11, s17
	s_cselect_b32 s20, s10, s16
	s_cselect_b32 s19, s13, s66
	s_cselect_b32 s18, s12, s63
	v_lshl_add_u64 v[150:151], s[14:15], 0, v[148:149]
	s_add_i32 m0, s29, 0xc000
	ds_read_b128 v[156:159], v155
	ds_read_b128 v[160:163], v155 offset:1024
	ds_read_b128 v[164:167], v155 offset:2048
	ds_read_b128 v[168:171], v155 offset:3072
	ds_read_b128 v[172:175], v155 offset:4096
	ds_read_b128 v[180:183], v155 offset:5120
	ds_read_b128 v[184:187], v155 offset:6144
	ds_read_b128 v[188:191], v155 offset:7168
	global_load_lds_dwordx4 v[150:151], off
	v_lshl_add_u64 v[150:151], s[14:15], 0, v[146:147]
	s_add_i32 m0, s29, 0xe000
	s_nop 0
	global_load_lds_dwordx4 v[150:151], off
	s_waitcnt lgkmcnt(8)
	s_barrier
	s_waitcnt lgkmcnt(0)
	v_mfma_f32_16x16x32_bf16 v[140:143], v[48:51], v[156:159], v[140:143]
	v_mfma_f32_16x16x32_bf16 v[136:139], v[72:75], v[156:159], v[136:139]
	v_mfma_f32_16x16x32_bf16 v[124:127], v[48:51], v[164:167], v[124:127]
	v_mfma_f32_16x16x32_bf16 v[120:123], v[72:75], v[164:167], v[120:123]
	v_mfma_f32_16x16x32_bf16 v[116:119], v[48:51], v[172:175], v[116:119]
	v_mfma_f32_16x16x32_bf16 v[112:115], v[72:75], v[172:175], v[112:115]
	v_mfma_f32_16x16x32_bf16 v[100:103], v[48:51], v[184:187], v[100:103]
	v_mfma_f32_16x16x32_bf16 v[96:99], v[72:75], v[184:187], v[96:99]
	v_mfma_f32_16x16x32_bf16 v[140:143], v[68:71], v[160:163], v[140:143]
	v_mfma_f32_16x16x32_bf16 v[136:139], v[76:79], v[160:163], v[136:139]
	v_mfma_f32_16x16x32_bf16 v[124:127], v[68:71], v[168:171], v[124:127]
	v_mfma_f32_16x16x32_bf16 v[120:123], v[76:79], v[168:171], v[120:123]
	v_mfma_f32_16x16x32_bf16 v[116:119], v[68:71], v[180:183], v[116:119]
	v_mfma_f32_16x16x32_bf16 v[112:115], v[76:79], v[180:183], v[112:115]
	v_mfma_f32_16x16x32_bf16 v[100:103], v[68:71], v[188:191], v[100:103]
	v_mfma_f32_16x16x32_bf16 v[96:99], v[76:79], v[188:191], v[96:99]
	s_barrier
	s_add_i32 s69, 0, 0x14000
	v_add_u32_e32 v150, s69, v153
	s_add_i32 s14, s68, s28
	ds_read_b128 v[192:195], v150
	ds_read_b128 v[196:199], v150 offset:1024
	ds_read_b128 v[204:207], v150 offset:2048
	ds_read_b128 v[212:215], v150 offset:3072
	s_mov_b32 m0, s14
	s_nop 0
	global_load_lds_dwordx4 v178, s[18:19]
	s_add_i32 m0, s14, 0x2000
	s_nop 0
	global_load_lds_dwordx4 v144, s[18:19]
	s_barrier
	s_waitcnt lgkmcnt(0)
	v_mfma_f32_16x16x32_bf16 v[132:135], v[192:195], v[156:159], v[132:135]
	v_mfma_f32_16x16x32_bf16 v[128:131], v[204:207], v[156:159], v[128:131]
	v_mfma_f32_16x16x32_bf16 v[108:111], v[192:195], v[164:167], v[108:111]
	v_mfma_f32_16x16x32_bf16 v[104:107], v[204:207], v[164:167], v[104:107]
	v_mfma_f32_16x16x32_bf16 v[92:95], v[192:195], v[172:175], v[92:95]
	v_mfma_f32_16x16x32_bf16 v[88:91], v[204:207], v[172:175], v[88:91]
	v_mfma_f32_16x16x32_bf16 v[84:87], v[192:195], v[184:187], v[84:87]
	v_mfma_f32_16x16x32_bf16 v[80:83], v[204:207], v[184:187], v[80:83]
	v_mfma_f32_16x16x32_bf16 v[132:135], v[196:199], v[160:163], v[132:135]
	v_mfma_f32_16x16x32_bf16 v[128:131], v[212:215], v[160:163], v[128:131]
	v_mfma_f32_16x16x32_bf16 v[108:111], v[196:199], v[168:171], v[108:111]
	v_mfma_f32_16x16x32_bf16 v[104:107], v[212:215], v[168:171], v[104:107]
	v_mfma_f32_16x16x32_bf16 v[92:95], v[196:199], v[180:183], v[92:95]
	v_mfma_f32_16x16x32_bf16 v[88:91], v[212:215], v[180:183], v[88:91]
	v_mfma_f32_16x16x32_bf16 v[84:87], v[196:199], v[188:191], v[84:87]
	v_mfma_f32_16x16x32_bf16 v[80:83], v[212:215], v[188:191], v[80:83]
	s_mov_b32 m0, s29
	s_mov_b64 s[100:101], s[20:21]
	s_barrier
	ds_read_b128 v[156:159], v155 offset:16384
	ds_read_b128 v[160:163], v155 offset:17408
	ds_read_b128 v[164:167], v155 offset:18432
	ds_read_b128 v[168:171], v155 offset:19456
	ds_read_b128 v[172:175], v155 offset:20480
	ds_read_b128 v[180:183], v155 offset:21504
	ds_read_b128 v[184:187], v155 offset:22528
	ds_read_b128 v[188:191], v155 offset:23552
	global_load_lds_dwordx4 v178, s[20:21]
	s_mov_b64 s[100:101], s[20:21]
	s_mov_b32 m0, s30
	s_nop 0
	global_load_lds_dwordx4 v144, s[20:21]
	s_barrier
	s_waitcnt lgkmcnt(0)
	v_mfma_f32_16x16x32_bf16 v[64:67], v[48:51], v[156:159], v[64:67]
	v_mfma_f32_16x16x32_bf16 v[60:63], v[72:75], v[156:159], v[60:63]
	v_mfma_f32_16x16x32_bf16 v[44:47], v[48:51], v[164:167], v[44:47]
	v_mfma_f32_16x16x32_bf16 v[40:43], v[72:75], v[164:167], v[40:43]
	v_mfma_f32_16x16x32_bf16 v[28:31], v[48:51], v[172:175], v[28:31]
	v_mfma_f32_16x16x32_bf16 v[24:27], v[72:75], v[172:175], v[24:27]
	v_mfma_f32_16x16x32_bf16 v[12:15], v[48:51], v[184:187], v[12:15]
	v_mfma_f32_16x16x32_bf16 v[8:11], v[72:75], v[184:187], v[8:11]
	v_mfma_f32_16x16x32_bf16 v[64:67], v[68:71], v[160:163], v[64:67]
	v_mfma_f32_16x16x32_bf16 v[60:63], v[76:79], v[160:163], v[60:63]
	v_mfma_f32_16x16x32_bf16 v[44:47], v[68:71], v[168:171], v[44:47]
	v_mfma_f32_16x16x32_bf16 v[40:43], v[76:79], v[168:171], v[40:43]
	v_mfma_f32_16x16x32_bf16 v[28:31], v[68:71], v[180:183], v[28:31]
	v_mfma_f32_16x16x32_bf16 v[24:27], v[76:79], v[180:183], v[24:27]
	v_mfma_f32_16x16x32_bf16 v[12:15], v[68:71], v[188:191], v[12:15]
	v_mfma_f32_16x16x32_bf16 v[8:11], v[76:79], v[188:191], v[8:11]
	s_barrier
	s_add_u32 s14, s18, 0x158000
	s_addc_u32 s15, s19, 0
	s_add_i32 s68, s69, s28
	s_mov_b32 m0, s68
	s_nop 0
	global_load_lds_dwordx4 v178, s[14:15]
	s_add_i32 m0, s68, 0x2000
	s_nop 0
	global_load_lds_dwordx4 v144, s[14:15]
	s_waitcnt vmcnt(6)
	s_barrier
	v_mfma_f32_16x16x32_bf16 v[52:55], v[204:207], v[156:159], v[52:55]
	v_mfma_f32_16x16x32_bf16 v[36:39], v[192:195], v[164:167], v[36:39]
	v_mfma_f32_16x16x32_bf16 v[32:35], v[204:207], v[164:167], v[32:35]
	v_mfma_f32_16x16x32_bf16 v[20:23], v[192:195], v[172:175], v[20:23]
	v_mfma_f32_16x16x32_bf16 v[16:19], v[204:207], v[172:175], v[16:19]
	v_mfma_f32_16x16x32_bf16 v[4:7], v[192:195], v[184:187], v[4:7]
	v_mfma_f32_16x16x32_bf16 v[0:3], v[204:207], v[184:187], v[0:3]
	v_mfma_f32_16x16x32_bf16 v[48:51], v[192:195], v[156:159], v[56:59]
	v_mfma_f32_16x16x32_bf16 v[52:55], v[212:215], v[160:163], v[52:55]
	v_mfma_f32_16x16x32_bf16 v[36:39], v[196:199], v[168:171], v[36:39]
	v_mfma_f32_16x16x32_bf16 v[32:35], v[212:215], v[168:171], v[32:35]
	v_mfma_f32_16x16x32_bf16 v[20:23], v[196:199], v[180:183], v[20:23]
	v_mfma_f32_16x16x32_bf16 v[16:19], v[212:215], v[180:183], v[16:19]
	v_mfma_f32_16x16x32_bf16 v[4:7], v[196:199], v[188:191], v[4:7]
	v_mfma_f32_16x16x32_bf16 v[0:3], v[212:215], v[188:191], v[0:3]
	v_mfma_f32_16x16x32_bf16 v[48:51], v[196:199], v[160:163], v[48:51]
	s_add_i32 s68, 0, 0x18000
	v_add_u32_e32 v76, s68, v153
	s_barrier
	ds_read_b128 v[56:59], v76
	ds_read_b128 v[68:71], v76 offset:1024
	ds_read_b128 v[72:75], v76 offset:2048
	ds_read_b128 v[76:79], v76 offset:3072
	s_add_u32 s14, s20, 0x158000
	s_addc_u32 s15, s21, 0
	s_mov_b32 m0, s31
	ds_read_b128 v[156:159], v155 offset:32768
	ds_read_b128 v[160:163], v155 offset:33792
	ds_read_b128 v[164:167], v155 offset:34816
	ds_read_b128 v[168:171], v155 offset:35840
	ds_read_b128 v[172:175], v155 offset:36864
	ds_read_b128 v[180:183], v155 offset:37888
	ds_read_b128 v[184:187], v155 offset:38912
	ds_read_b128 v[188:191], v155 offset:39936
	global_load_lds_dwordx4 v178, s[14:15]
	s_mov_b32 m0, s34
	s_nop 0
	global_load_lds_dwordx4 v144, s[14:15]
	s_waitcnt lgkmcnt(8)
	s_barrier
	s_waitcnt lgkmcnt(0)
	v_mfma_f32_16x16x32_bf16 v[140:143], v[56:59], v[156:159], v[140:143]
	v_mfma_f32_16x16x32_bf16 v[136:139], v[72:75], v[156:159], v[136:139]
	v_mfma_f32_16x16x32_bf16 v[124:127], v[56:59], v[164:167], v[124:127]
	v_mfma_f32_16x16x32_bf16 v[120:123], v[72:75], v[164:167], v[120:123]
	v_mfma_f32_16x16x32_bf16 v[116:119], v[56:59], v[172:175], v[116:119]
	v_mfma_f32_16x16x32_bf16 v[112:115], v[72:75], v[172:175], v[112:115]
	v_mfma_f32_16x16x32_bf16 v[100:103], v[56:59], v[184:187], v[100:103]
	v_mfma_f32_16x16x32_bf16 v[96:99], v[72:75], v[184:187], v[96:99]
	v_mfma_f32_16x16x32_bf16 v[140:143], v[68:71], v[160:163], v[140:143]
	v_mfma_f32_16x16x32_bf16 v[136:139], v[76:79], v[160:163], v[136:139]
	v_mfma_f32_16x16x32_bf16 v[124:127], v[68:71], v[168:171], v[124:127]
	v_mfma_f32_16x16x32_bf16 v[120:123], v[76:79], v[168:171], v[120:123]
	v_mfma_f32_16x16x32_bf16 v[116:119], v[68:71], v[180:183], v[116:119]
	v_mfma_f32_16x16x32_bf16 v[112:115], v[76:79], v[180:183], v[112:115]
	v_mfma_f32_16x16x32_bf16 v[100:103], v[68:71], v[188:191], v[100:103]
	v_mfma_f32_16x16x32_bf16 v[96:99], v[76:79], v[188:191], v[96:99]
	s_barrier
	s_add_i32 s20, 0, 0x1c000
	s_add_i32 s14, s68, s28
	v_add_u32_e32 v212, s20, v153
	s_add_i32 m0, s14, 0xffffff80
	ds_read_b128 v[192:195], v212
	ds_read_b128 v[196:199], v212 offset:1024
	ds_read_b128 v[204:207], v212 offset:2048
	ds_read_b128 v[212:215], v212 offset:3072
	global_load_lds_dwordx4 v178, s[18:19] offset:128
	s_add_i32 m0, s14, 0x1f80
	s_nop 0
	global_load_lds_dwordx4 v144, s[18:19] offset:128
	s_barrier
	s_waitcnt lgkmcnt(0)
	v_mfma_f32_16x16x32_bf16 v[132:135], v[192:195], v[156:159], v[132:135]
	v_mfma_f32_16x16x32_bf16 v[128:131], v[204:207], v[156:159], v[128:131]
	v_mfma_f32_16x16x32_bf16 v[108:111], v[192:195], v[164:167], v[108:111]
	v_mfma_f32_16x16x32_bf16 v[104:107], v[204:207], v[164:167], v[104:107]
	v_mfma_f32_16x16x32_bf16 v[92:95], v[192:195], v[172:175], v[92:95]
	v_mfma_f32_16x16x32_bf16 v[88:91], v[204:207], v[172:175], v[88:91]
	v_mfma_f32_16x16x32_bf16 v[84:87], v[192:195], v[184:187], v[84:87]
	v_mfma_f32_16x16x32_bf16 v[80:83], v[204:207], v[184:187], v[80:83]
	v_mfma_f32_16x16x32_bf16 v[132:135], v[196:199], v[160:163], v[132:135]
	v_mfma_f32_16x16x32_bf16 v[128:131], v[212:215], v[160:163], v[128:131]
	v_mfma_f32_16x16x32_bf16 v[108:111], v[196:199], v[168:171], v[108:111]
	v_mfma_f32_16x16x32_bf16 v[104:107], v[212:215], v[168:171], v[104:107]
	v_mfma_f32_16x16x32_bf16 v[92:95], v[196:199], v[180:183], v[92:95]
	v_mfma_f32_16x16x32_bf16 v[88:91], v[212:215], v[180:183], v[88:91]
	v_mfma_f32_16x16x32_bf16 v[84:87], v[196:199], v[188:191], v[84:87]
	v_mfma_f32_16x16x32_bf16 v[80:83], v[212:215], v[188:191], v[80:83]
	s_add_i32 m0, s56, 0xffffff80
	s_barrier
	ds_read_b128 v[156:159], v155 offset:49152
	ds_read_b128 v[160:163], v155 offset:50176
	ds_read_b128 v[164:167], v155 offset:51200
	ds_read_b128 v[168:171], v155 offset:52224
	ds_read_b128 v[172:175], v155 offset:53248
	ds_read_b128 v[180:183], v155 offset:54272
	ds_read_b128 v[184:187], v155 offset:55296
	ds_read_b128 v[188:191], v155 offset:56320
	global_load_lds_dwordx4 v178, s[100:101] offset:128
	s_add_i32 m0, s57, 0xffffff80
	s_nop 0
	global_load_lds_dwordx4 v144, s[100:101] offset:128
	s_barrier
	s_waitcnt lgkmcnt(0)
	v_mfma_f32_16x16x32_bf16 v[64:67], v[56:59], v[156:159], v[64:67]
	v_mfma_f32_16x16x32_bf16 v[60:63], v[72:75], v[156:159], v[60:63]
	v_mfma_f32_16x16x32_bf16 v[44:47], v[56:59], v[164:167], v[44:47]
	v_mfma_f32_16x16x32_bf16 v[40:43], v[72:75], v[164:167], v[40:43]
	v_mfma_f32_16x16x32_bf16 v[28:31], v[56:59], v[172:175], v[28:31]
	v_mfma_f32_16x16x32_bf16 v[24:27], v[72:75], v[172:175], v[24:27]
	v_mfma_f32_16x16x32_bf16 v[12:15], v[56:59], v[184:187], v[12:15]
	v_mfma_f32_16x16x32_bf16 v[8:11], v[72:75], v[184:187], v[8:11]
	v_mfma_f32_16x16x32_bf16 v[64:67], v[68:71], v[160:163], v[64:67]
	v_mfma_f32_16x16x32_bf16 v[60:63], v[76:79], v[160:163], v[60:63]
	v_mfma_f32_16x16x32_bf16 v[44:47], v[68:71], v[168:171], v[44:47]
	v_mfma_f32_16x16x32_bf16 v[40:43], v[76:79], v[168:171], v[40:43]
	v_mfma_f32_16x16x32_bf16 v[28:31], v[68:71], v[180:183], v[28:31]
	v_mfma_f32_16x16x32_bf16 v[24:27], v[76:79], v[180:183], v[24:27]
	v_mfma_f32_16x16x32_bf16 v[12:15], v[68:71], v[188:191], v[12:15]
	v_mfma_f32_16x16x32_bf16 v[8:11], v[76:79], v[188:191], v[8:11]
	s_barrier
	s_add_u32 s14, s18, 0x158080
	s_addc_u32 s15, s19, 0
	s_add_i32 s18, s20, s28
	s_mov_b32 m0, s18
	s_nop 0
	global_load_lds_dwordx4 v178, s[14:15]
	s_add_i32 m0, s18, 0x2000
	s_nop 0
	global_load_lds_dwordx4 v144, s[14:15]
	s_waitcnt vmcnt(6)
	s_barrier
	v_mfma_f32_16x16x32_bf16 v[48:51], v[192:195], v[156:159], v[48:51]
	v_mfma_f32_16x16x32_bf16 v[56:59], v[196:199], v[160:163], v[48:51]
	v_mfma_f32_16x16x32_bf16 v[48:51], v[204:207], v[156:159], v[52:55]
	v_mfma_f32_16x16x32_bf16 v[36:39], v[192:195], v[164:167], v[36:39]
	v_mfma_f32_16x16x32_bf16 v[32:35], v[204:207], v[164:167], v[32:35]
	v_mfma_f32_16x16x32_bf16 v[20:23], v[192:195], v[172:175], v[20:23]
	v_mfma_f32_16x16x32_bf16 v[16:19], v[204:207], v[172:175], v[16:19]
	v_mfma_f32_16x16x32_bf16 v[4:7], v[192:195], v[184:187], v[4:7]
	v_mfma_f32_16x16x32_bf16 v[0:3], v[204:207], v[184:187], v[0:3]
	v_mfma_f32_16x16x32_bf16 v[52:55], v[212:215], v[160:163], v[48:51]
	v_mfma_f32_16x16x32_bf16 v[36:39], v[196:199], v[168:171], v[36:39]
	v_mfma_f32_16x16x32_bf16 v[32:35], v[212:215], v[168:171], v[32:35]
	v_mfma_f32_16x16x32_bf16 v[20:23], v[196:199], v[180:183], v[20:23]
	v_mfma_f32_16x16x32_bf16 v[16:19], v[212:215], v[180:183], v[16:19]
	v_mfma_f32_16x16x32_bf16 v[4:7], v[196:199], v[188:191], v[4:7]
	v_mfma_f32_16x16x32_bf16 v[0:3], v[212:215], v[188:191], v[0:3]
	s_add_i32 s67, s67, 2
	s_add_u32 s63, s63, 0x100
	s_addc_u32 s66, s66, 0
	s_cmpk_gt_u32 s67, 0x53
	s_mov_b64 s[14:15], s[16:17]
	s_barrier
	s_cbranch_scc0 .LBB0_1363
	s_lshl_b32 s12, s61, 8
	s_add_i32 s10, s12, 0xfffff000
	s_ashr_i32 s10, s10, 11
	s_add_i32 s10, s10, 1
	s_cmp_gt_i32 s61, 15
	s_cselect_b32 s10, s10, 0
	v_add_u32_e32 v162, s12, v152
	v_lshl_or_b32 v48, s62, 8, v154
	s_mul_hi_i32 s11, s10, 0xc000
	s_mul_i32 s10, s10, 0xc000
	v_ashrrev_i32_e32 v163, 31, v162
	v_readlane_b32 s68, v252, 37
	s_add_u32 s10, s35, s10
	v_ashrrev_i32_e32 v49, 31, v48
	v_lshlrev_b64 v[150:151], 13, v[162:163]
	v_readlane_b32 s82, v252, 51
	v_readlane_b32 s83, v252, 52
	s_addc_u32 s11, s39, s11
	v_lshlrev_b64 v[160:161], 2, v[48:49]
	v_lshl_add_u64 v[150:151], s[82:83], 0, v[150:151]
	v_lshl_add_u64 v[48:49], s[10:11], 0, v[160:161]
	v_lshl_add_u64 v[150:151], v[150:151], 0, v[160:161]
	global_load_dwordx4 v[76:79], v[48:49], off
	global_load_dwordx4 v[72:75], v[48:49], off offset:64
	global_load_dwordx4 v[68:71], v[48:49], off offset:512
	s_nop 0
	global_load_dwordx4 v[48:51], v[48:49], off offset:576
	s_mov_b64 s[10:11], 0x100000
	s_mov_b32 s62, s59
	s_mov_b32 s61, s60
	s_mov_b64 s[16:17], s[6:7]
	s_mov_b64 s[14:15], s[8:9]
	v_readlane_b32 s69, v252, 38
	v_readlane_b32 s70, v252, 39
	v_readlane_b32 s71, v252, 40
	v_readlane_b32 s72, v252, 41
	v_readlane_b32 s73, v252, 42
	v_readlane_b32 s74, v252, 43
	v_readlane_b32 s75, v252, 44
	v_readlane_b32 s76, v252, 45
	v_readlane_b32 s77, v252, 46
	v_readlane_b32 s78, v252, 47
	v_readlane_b32 s79, v252, 48
	v_readlane_b32 s80, v252, 49
	v_readlane_b32 s81, v252, 50
	s_and_b64 vcc, exec, s[4:5]
	s_nop 4
	v_lshl_add_u32 v145, v162, 13, v160
	v_add_u32_e32 v156, 0x20000, v145
	v_add_u32_e32 v158, 0x40000, v145
	v_add_u32_e32 v159, 0x60000, v145
	v_add_u32_e32 v176, 0x100000, v145
	v_add_u32_e32 v177, 0x120000, v145
	v_add_u32_e32 v223, 0x140000, v145
	v_add_u32_e32 v248, 0x160000, v145
	global_load_dwordx4 v[164:167], v145, s[82:83]
	global_load_dwordx4 v[168:171], v145, s[82:83] offset:64
	global_load_dwordx4 v[172:175], v145, s[82:83] offset:512
	global_load_dwordx4 v[180:183], v145, s[82:83] offset:576
	global_load_dwordx4 v[184:187], v156, s[82:83]
	global_load_dwordx4 v[188:191], v156, s[82:83] offset:64
	global_load_dwordx4 v[192:195], v156, s[82:83] offset:512
	global_load_dwordx4 v[196:199], v156, s[82:83] offset:576
	global_load_dwordx4 v[204:207], v158, s[82:83]
	global_load_dwordx4 v[212:215], v158, s[82:83] offset:64
	global_load_dwordx4 v[224:227], v158, s[82:83] offset:512
	global_load_dwordx4 v[228:231], v158, s[82:83] offset:576
	global_load_dwordx4 v[232:235], v159, s[82:83]
	global_load_dwordx4 v[236:239], v159, s[82:83] offset:64
	global_load_dwordx4 v[240:243], v159, s[82:83] offset:512
	global_load_dwordx4 v[244:247], v159, s[82:83] offset:576
	s_waitcnt vmcnt(15)
	v_pk_fma_f32 v[142:143], v[142:143], v[78:79], v[166:167]
	v_pk_fma_f32 v[140:141], v[140:141], v[76:77], v[164:165]
	global_store_dwordx4 v145, v[140:143], s[82:83]
	global_load_dwordx4 v[164:167], v176, s[82:83]
	s_waitcnt vmcnt(16)
	v_pk_fma_f32 v[138:139], v[138:139], v[74:75], v[170:171]
	v_pk_fma_f32 v[136:137], v[136:137], v[72:73], v[168:169]
	global_store_dwordx4 v145, v[136:139], s[82:83] offset:64
	global_load_dwordx4 v[168:171], v176, s[82:83] offset:64
	s_waitcnt vmcnt(17)
	v_pk_fma_f32 v[134:135], v[134:135], v[70:71], v[174:175]
	v_pk_fma_f32 v[132:133], v[132:133], v[68:69], v[172:173]
	global_store_dwordx4 v145, v[132:135], s[82:83] offset:512
	global_load_dwordx4 v[172:175], v176, s[82:83] offset:512
	s_waitcnt vmcnt(18)
	v_pk_fma_f32 v[130:131], v[130:131], v[50:51], v[182:183]
	v_pk_fma_f32 v[128:129], v[128:129], v[48:49], v[180:181]
	global_store_dwordx4 v145, v[128:131], s[82:83] offset:576
	global_load_dwordx4 v[180:183], v176, s[82:83] offset:576
	s_waitcnt vmcnt(19)
	v_pk_fma_f32 v[126:127], v[126:127], v[78:79], v[186:187]
	v_pk_fma_f32 v[124:125], v[124:125], v[76:77], v[184:185]
	global_store_dwordx4 v156, v[124:127], s[82:83]
	global_load_dwordx4 v[184:187], v177, s[82:83]
	s_waitcnt vmcnt(20)
	v_pk_fma_f32 v[122:123], v[122:123], v[74:75], v[190:191]
	v_pk_fma_f32 v[120:121], v[120:121], v[72:73], v[188:189]
	global_store_dwordx4 v156, v[120:123], s[82:83] offset:64
	global_load_dwordx4 v[188:191], v177, s[82:83] offset:64
	s_waitcnt vmcnt(21)
	v_pk_fma_f32 v[110:111], v[110:111], v[70:71], v[194:195]
	v_pk_fma_f32 v[108:109], v[108:109], v[68:69], v[192:193]
	global_store_dwordx4 v156, v[108:111], s[82:83] offset:512
	global_load_dwordx4 v[192:195], v177, s[82:83] offset:512
	s_waitcnt vmcnt(22)
	v_pk_fma_f32 v[106:107], v[106:107], v[50:51], v[198:199]
	v_pk_fma_f32 v[104:105], v[104:105], v[48:49], v[196:197]
	global_store_dwordx4 v156, v[104:107], s[82:83] offset:576
	global_load_dwordx4 v[196:199], v177, s[82:83] offset:576
	s_waitcnt vmcnt(23)
	v_pk_fma_f32 v[118:119], v[118:119], v[78:79], v[206:207]
	v_pk_fma_f32 v[116:117], v[116:117], v[76:77], v[204:205]
	global_store_dwordx4 v158, v[116:119], s[82:83]
	global_load_dwordx4 v[204:207], v223, s[82:83]
	s_waitcnt vmcnt(24)
	v_pk_fma_f32 v[114:115], v[114:115], v[74:75], v[214:215]
	v_pk_fma_f32 v[112:113], v[112:113], v[72:73], v[212:213]
	global_store_dwordx4 v158, v[112:115], s[82:83] offset:64
	global_load_dwordx4 v[212:215], v223, s[82:83] offset:64
	s_waitcnt vmcnt(25)
	v_pk_fma_f32 v[94:95], v[94:95], v[70:71], v[226:227]
	v_pk_fma_f32 v[92:93], v[92:93], v[68:69], v[224:225]
	global_store_dwordx4 v158, v[92:95], s[82:83] offset:512
	global_load_dwordx4 v[224:227], v223, s[82:83] offset:512
	s_waitcnt vmcnt(26)
	v_pk_fma_f32 v[90:91], v[90:91], v[50:51], v[230:231]
	v_pk_fma_f32 v[88:89], v[88:89], v[48:49], v[228:229]
	global_store_dwordx4 v158, v[88:91], s[82:83] offset:576
	global_load_dwordx4 v[228:231], v223, s[82:83] offset:576
	s_waitcnt vmcnt(27)
	v_pk_fma_f32 v[102:103], v[102:103], v[78:79], v[234:235]
	v_pk_fma_f32 v[100:101], v[100:101], v[76:77], v[232:233]
	global_store_dwordx4 v159, v[100:103], s[82:83]
	global_load_dwordx4 v[232:235], v248, s[82:83]
	s_waitcnt vmcnt(28)
	v_pk_fma_f32 v[98:99], v[98:99], v[74:75], v[238:239]
	v_pk_fma_f32 v[96:97], v[96:97], v[72:73], v[236:237]
	global_store_dwordx4 v159, v[96:99], s[82:83] offset:64
	global_load_dwordx4 v[236:239], v248, s[82:83] offset:64
	s_waitcnt vmcnt(29)
	v_pk_fma_f32 v[86:87], v[86:87], v[70:71], v[242:243]
	v_pk_fma_f32 v[84:85], v[84:85], v[68:69], v[240:241]
	global_store_dwordx4 v159, v[84:87], s[82:83] offset:512
	global_load_dwordx4 v[240:243], v248, s[82:83] offset:512
	s_waitcnt vmcnt(30)
	v_pk_fma_f32 v[82:83], v[82:83], v[50:51], v[246:247]
	v_pk_fma_f32 v[80:81], v[80:81], v[48:49], v[244:245]
	global_store_dwordx4 v159, v[80:83], s[82:83] offset:576
	global_load_dwordx4 v[244:247], v248, s[82:83] offset:576
	s_waitcnt vmcnt(30)
	v_pk_fma_f32 v[66:67], v[66:67], v[78:79], v[166:167]
	v_pk_fma_f32 v[64:65], v[64:65], v[76:77], v[164:165]
	global_store_dwordx4 v176, v[64:67], s[82:83]
	s_waitcnt vmcnt(29)
	v_pk_fma_f32 v[62:63], v[62:63], v[74:75], v[170:171]
	v_pk_fma_f32 v[60:61], v[60:61], v[72:73], v[168:169]
	global_store_dwordx4 v176, v[60:63], s[82:83] offset:64
	s_waitcnt vmcnt(28)
	v_pk_fma_f32 v[58:59], v[58:59], v[70:71], v[174:175]
	v_pk_fma_f32 v[56:57], v[56:57], v[68:69], v[172:173]
	global_store_dwordx4 v176, v[56:59], s[82:83] offset:512
	s_waitcnt vmcnt(27)
	v_pk_fma_f32 v[54:55], v[54:55], v[50:51], v[182:183]
	v_pk_fma_f32 v[52:53], v[52:53], v[48:49], v[180:181]
	global_store_dwordx4 v176, v[52:55], s[82:83] offset:576
	s_waitcnt vmcnt(26)
	v_pk_fma_f32 v[46:47], v[46:47], v[78:79], v[186:187]
	v_pk_fma_f32 v[44:45], v[44:45], v[76:77], v[184:185]
	global_store_dwordx4 v177, v[44:47], s[82:83]
	s_waitcnt vmcnt(25)
	v_pk_fma_f32 v[42:43], v[42:43], v[74:75], v[190:191]
	v_pk_fma_f32 v[40:41], v[40:41], v[72:73], v[188:189]
	global_store_dwordx4 v177, v[40:43], s[82:83] offset:64
	s_waitcnt vmcnt(24)
	v_pk_fma_f32 v[38:39], v[38:39], v[70:71], v[194:195]
	v_pk_fma_f32 v[36:37], v[36:37], v[68:69], v[192:193]
	global_store_dwordx4 v177, v[36:39], s[82:83] offset:512
	s_waitcnt vmcnt(23)
	v_pk_fma_f32 v[34:35], v[34:35], v[50:51], v[198:199]
	v_pk_fma_f32 v[32:33], v[32:33], v[48:49], v[196:197]
	global_store_dwordx4 v177, v[32:35], s[82:83] offset:576
	s_waitcnt vmcnt(22)
	v_pk_fma_f32 v[30:31], v[30:31], v[78:79], v[206:207]
	v_pk_fma_f32 v[28:29], v[28:29], v[76:77], v[204:205]
	global_store_dwordx4 v223, v[28:31], s[82:83]
	s_waitcnt vmcnt(21)
	v_pk_fma_f32 v[26:27], v[26:27], v[74:75], v[214:215]
	v_pk_fma_f32 v[24:25], v[24:25], v[72:73], v[212:213]
	global_store_dwordx4 v223, v[24:27], s[82:83] offset:64
	s_waitcnt vmcnt(20)
	v_pk_fma_f32 v[22:23], v[22:23], v[70:71], v[226:227]
	v_pk_fma_f32 v[20:21], v[20:21], v[68:69], v[224:225]
	global_store_dwordx4 v223, v[20:23], s[82:83] offset:512
	s_waitcnt vmcnt(19)
	v_pk_fma_f32 v[18:19], v[18:19], v[50:51], v[230:231]
	v_pk_fma_f32 v[16:17], v[16:17], v[48:49], v[228:229]
	global_store_dwordx4 v223, v[16:19], s[82:83] offset:576
	s_waitcnt vmcnt(18)
	v_pk_fma_f32 v[14:15], v[14:15], v[78:79], v[234:235]
	v_pk_fma_f32 v[12:13], v[12:13], v[76:77], v[232:233]
	global_store_dwordx4 v248, v[12:15], s[82:83]
	s_waitcnt vmcnt(17)
	v_pk_fma_f32 v[10:11], v[10:11], v[74:75], v[238:239]
	v_pk_fma_f32 v[8:9], v[8:9], v[72:73], v[236:237]
	global_store_dwordx4 v248, v[8:11], s[82:83] offset:64
	s_waitcnt vmcnt(16)
	v_pk_fma_f32 v[6:7], v[6:7], v[70:71], v[242:243]
	v_pk_fma_f32 v[4:5], v[4:5], v[68:69], v[240:241]
	global_store_dwordx4 v248, v[4:7], s[82:83] offset:512
	s_waitcnt vmcnt(15)
	v_pk_fma_f32 v[2:3], v[2:3], v[50:51], v[246:247]
	v_pk_fma_f32 v[0:1], v[0:1], v[48:49], v[244:245]
	global_store_dwordx4 v248, v[0:3], s[82:83] offset:576
	s_mov_b64 s[10:11], 0x160000
	s_cbranch_vccz .LBB0_1360
	s_waitcnt vmcnt(0)
	s_mov_b32 s4, s86
	s_cmp_gt_u32 s4, 3
	s_movk_i32 s57, 0x404
	s_cbranch_scc1 .LBB0_1367
	s_barrier
